# GEMM K-loops: s_setprio 1 raised before parking at the pre-MFMA barrier and the redundant compiler lgkmcnt(0) after it removed (inline-asm lgkmcnt(0) already precedes the barrier), 24 sites
# speedup vs baseline: 1.0111x; 1.0088x over previous
.LBB0_180:
	s_add_u32 s12, s26, s8
	s_addc_u32 s13, s27, s9
	s_add_u32 s12, s12, 0x100
	s_addc_u32 s13, s13, 0
	s_add_u32 s81, s67, s8
	s_addc_u32 s83, s43, s9
	s_add_i32 s95, 0, 0x10000
	s_cmpk_eq_i32 s8, 0xf00
	s_cselect_b32 s35, s25, s13
	s_cselect_b32 s34, s36, s12
	s_cselect_b32 s13, s23, s83
	s_cselect_b32 s12, s37, s81
	s_add_i32 s81, 0, 0x14000
	v_add_u32_e32 v148, s95, v230
	v_add_u32_e32 v164, s81, v230
	ds_read_b128 v[136:139], v148
	ds_read_b128 v[140:143], v148 offset:1024
	ds_read_b128 v[144:147], v148 offset:2048
	ds_read_b128 v[148:151], v148 offset:3072
	ds_read_b128 v[152:155], v164
	ds_read_b128 v[156:159], v164 offset:1024
	ds_read_b128 v[160:163], v164 offset:2048
	ds_read_b128 v[164:167], v164 offset:3072
	v_lshl_add_u64 v[196:197], v[132:133], 0, s[8:9]
	s_add_i32 m0, s39, 0xc000
	ds_read_b128 v[168:171], v242
	ds_read_b128 v[188:191], v242 offset:1024
	ds_read_b128 v[192:195], v242 offset:2048
	ds_read_b128 v[204:207], v242 offset:3072
	ds_read_b128 v[208:211], v242 offset:4096
	ds_read_b128 v[212:215], v242 offset:5120
	ds_read_b128 v[244:247], v242 offset:6144
	ds_read_b128 v[248:251], v242 offset:7168
	global_load_lds_dwordx4 v[196:197], off
	v_lshl_add_u64 v[196:197], v[134:135], 0, s[8:9]
	s_add_i32 m0, s39, 0xe000
	s_nop 0
	global_load_lds_dwordx4 v[196:197], off
	s_waitcnt vmcnt(8)
	s_waitcnt lgkmcnt(0)
	s_setprio 1
	s_barrier
	v_mfma_f32_16x16x32_bf16 v[8:11], v[136:139], v[168:171], v[8:11]
	v_mfma_f32_16x16x32_bf16 v[128:131], v[144:147], v[168:171], v[128:131]
	v_mfma_f32_16x16x32_bf16 v[124:127], v[136:139], v[192:195], v[124:127]
	v_mfma_f32_16x16x32_bf16 v[120:123], v[144:147], v[192:195], v[120:123]
	v_mfma_f32_16x16x32_bf16 v[116:119], v[136:139], v[208:211], v[116:119]
	v_mfma_f32_16x16x32_bf16 v[112:115], v[144:147], v[208:211], v[112:115]
	v_mfma_f32_16x16x32_bf16 v[108:111], v[136:139], v[244:247], v[108:111]
	v_mfma_f32_16x16x32_bf16 v[104:107], v[144:147], v[244:247], v[104:107]
	v_mfma_f32_16x16x32_bf16 v[8:11], v[140:143], v[188:191], v[8:11]
	v_mfma_f32_16x16x32_bf16 v[128:131], v[148:151], v[188:191], v[128:131]
	v_mfma_f32_16x16x32_bf16 v[124:127], v[140:143], v[204:207], v[124:127]
	v_mfma_f32_16x16x32_bf16 v[120:123], v[148:151], v[204:207], v[120:123]
	v_mfma_f32_16x16x32_bf16 v[116:119], v[140:143], v[212:215], v[116:119]
	v_mfma_f32_16x16x32_bf16 v[112:115], v[148:151], v[212:215], v[112:115]
	v_mfma_f32_16x16x32_bf16 v[108:111], v[140:143], v[248:251], v[108:111]
	v_mfma_f32_16x16x32_bf16 v[104:107], v[148:151], v[248:251], v[104:107]
	s_setprio 0
	s_setprio 1
	v_mfma_f32_16x16x32_bf16 v[100:103], v[152:155], v[168:171], v[100:103]
	v_mfma_f32_16x16x32_bf16 v[96:99], v[160:163], v[168:171], v[96:99]
	v_mfma_f32_16x16x32_bf16 v[92:95], v[152:155], v[192:195], v[92:95]
	v_mfma_f32_16x16x32_bf16 v[88:91], v[160:163], v[192:195], v[88:91]
	v_mfma_f32_16x16x32_bf16 v[84:87], v[152:155], v[208:211], v[84:87]
	v_mfma_f32_16x16x32_bf16 v[80:83], v[160:163], v[208:211], v[80:83]
	v_mfma_f32_16x16x32_bf16 v[76:79], v[152:155], v[244:247], v[76:79]
	v_mfma_f32_16x16x32_bf16 v[72:75], v[160:163], v[244:247], v[72:75]
	v_mfma_f32_16x16x32_bf16 v[100:103], v[156:159], v[188:191], v[100:103]
	v_mfma_f32_16x16x32_bf16 v[96:99], v[164:167], v[188:191], v[96:99]
	v_mfma_f32_16x16x32_bf16 v[92:95], v[156:159], v[204:207], v[92:95]
	v_mfma_f32_16x16x32_bf16 v[88:91], v[164:167], v[204:207], v[88:91]
	v_mfma_f32_16x16x32_bf16 v[84:87], v[156:159], v[212:215], v[84:87]
	v_mfma_f32_16x16x32_bf16 v[80:83], v[164:167], v[212:215], v[80:83]
	v_mfma_f32_16x16x32_bf16 v[76:79], v[156:159], v[248:251], v[76:79]
	v_mfma_f32_16x16x32_bf16 v[72:75], v[164:167], v[248:251], v[72:75]
	s_setprio 0
	s_barrier
	s_add_i32 s83, s95, s38
	v_lshl_add_u64 v[196:197], s[12:13], 0, v[172:173]
	s_mov_b32 m0, s83
	ds_read_b128 v[168:171], v242 offset:16384
	ds_read_b128 v[188:191], v242 offset:17408
	ds_read_b128 v[192:195], v242 offset:18432
	ds_read_b128 v[204:207], v242 offset:19456
	ds_read_b128 v[208:211], v242 offset:20480
	ds_read_b128 v[212:215], v242 offset:21504
	ds_read_b128 v[244:247], v242 offset:22528
	ds_read_b128 v[248:251], v242 offset:23552
	global_load_lds_dwordx4 v[196:197], off
	s_add_i32 m0, s83, 0x2000
	s_add_u32 vcc_lo, s12, 0x80000
	v_lshl_add_u64 v[198:199], s[12:13], 0, v[176:177]
	s_addc_u32 vcc_hi, s13, 0
	s_add_i32 s81, s81, s38
	global_load_lds_dwordx4 v[198:199], off
	v_lshl_add_u64 v[200:201], vcc, 0, v[172:173]
	s_mov_b32 m0, s81
	v_lshl_add_u64 v[202:203], s[34:35], 0, v[174:175]
	global_load_lds_dwordx4 v[200:201], off
	v_lshl_add_u64 v[200:201], vcc, 0, v[176:177]
	s_add_i32 m0, s81, 0x2000
	s_nop 0
	global_load_lds_dwordx4 v[200:201], off
	v_lshl_add_u64 v[200:201], s[34:35], 0, v[0:1]
	s_mov_b32 m0, s39
	s_nop 0
	global_load_lds_dwordx4 v[200:201], off
	s_mov_b32 m0, s46
	s_nop 0
	global_load_lds_dwordx4 v[202:203], off
	s_waitcnt vmcnt(8)
	s_waitcnt lgkmcnt(0)
	s_setprio 1
	s_barrier
	v_mfma_f32_16x16x32_bf16 v[68:71], v[136:139], v[168:171], v[68:71]
	v_mfma_f32_16x16x32_bf16 v[64:67], v[144:147], v[168:171], v[64:67]
	v_mfma_f32_16x16x32_bf16 v[60:63], v[136:139], v[192:195], v[60:63]
	v_mfma_f32_16x16x32_bf16 v[56:59], v[144:147], v[192:195], v[56:59]
	v_mfma_f32_16x16x32_bf16 v[52:55], v[136:139], v[208:211], v[52:55]
	v_mfma_f32_16x16x32_bf16 v[48:51], v[144:147], v[208:211], v[48:51]
	v_mfma_f32_16x16x32_bf16 v[44:47], v[136:139], v[244:247], v[44:47]
	v_mfma_f32_16x16x32_bf16 v[40:43], v[144:147], v[244:247], v[40:43]
	v_mfma_f32_16x16x32_bf16 v[68:71], v[140:143], v[188:191], v[68:71]
	v_mfma_f32_16x16x32_bf16 v[64:67], v[148:151], v[188:191], v[64:67]
	v_mfma_f32_16x16x32_bf16 v[60:63], v[140:143], v[204:207], v[60:63]
	v_mfma_f32_16x16x32_bf16 v[56:59], v[148:151], v[204:207], v[56:59]
	v_mfma_f32_16x16x32_bf16 v[52:55], v[140:143], v[212:215], v[52:55]
	v_mfma_f32_16x16x32_bf16 v[48:51], v[148:151], v[212:215], v[48:51]
	v_mfma_f32_16x16x32_bf16 v[44:47], v[140:143], v[248:251], v[44:47]
	v_mfma_f32_16x16x32_bf16 v[40:43], v[148:151], v[248:251], v[40:43]
	s_setprio 0
	s_setprio 1
	v_mfma_f32_16x16x32_bf16 v[36:39], v[152:155], v[168:171], v[36:39]
	v_mfma_f32_16x16x32_bf16 v[32:35], v[160:163], v[168:171], v[32:35]
	v_mfma_f32_16x16x32_bf16 v[28:31], v[152:155], v[192:195], v[28:31]
	v_mfma_f32_16x16x32_bf16 v[24:27], v[160:163], v[192:195], v[24:27]
	v_mfma_f32_16x16x32_bf16 v[20:23], v[152:155], v[208:211], v[20:23]
	v_mfma_f32_16x16x32_bf16 v[16:19], v[160:163], v[208:211], v[16:19]
	v_mfma_f32_16x16x32_bf16 v[12:15], v[152:155], v[244:247], v[12:15]
	v_mfma_f32_16x16x32_bf16 v[4:7], v[160:163], v[244:247], v[4:7]
	v_mfma_f32_16x16x32_bf16 v[36:39], v[156:159], v[188:191], v[36:39]
	v_mfma_f32_16x16x32_bf16 v[32:35], v[164:167], v[188:191], v[32:35]
	v_mfma_f32_16x16x32_bf16 v[28:31], v[156:159], v[204:207], v[28:31]
	v_mfma_f32_16x16x32_bf16 v[24:27], v[164:167], v[204:207], v[24:27]
	v_mfma_f32_16x16x32_bf16 v[20:23], v[156:159], v[212:215], v[20:23]
	v_mfma_f32_16x16x32_bf16 v[16:19], v[164:167], v[212:215], v[16:19]
	v_mfma_f32_16x16x32_bf16 v[12:15], v[156:159], v[248:251], v[12:15]
	v_mfma_f32_16x16x32_bf16 v[4:7], v[164:167], v[248:251], v[4:7]
	s_setprio 0
	s_barrier
	s_add_i32 s81, 0, 0x18000
	s_add_i32 s83, 0, 0x1c000
	v_add_u32_e32 v148, s81, v230
	v_add_u32_e32 v164, s83, v230
	ds_read_b128 v[136:139], v148
	ds_read_b128 v[140:143], v148 offset:1024
	ds_read_b128 v[144:147], v148 offset:2048
	ds_read_b128 v[148:151], v148 offset:3072
	ds_read_b128 v[152:155], v164
	ds_read_b128 v[156:159], v164 offset:1024
	ds_read_b128 v[160:163], v164 offset:2048
	ds_read_b128 v[164:167], v164 offset:3072
	s_add_u32 s34, s34, 0x80000
	s_addc_u32 s35, s35, 0
	s_mov_b32 m0, s47
	v_lshl_add_u64 v[216:217], s[34:35], 0, v[0:1]
	ds_read_b128 v[168:171], v242 offset:32768
	ds_read_b128 v[188:191], v242 offset:33792
	ds_read_b128 v[192:195], v242 offset:34816
	ds_read_b128 v[204:207], v242 offset:35840
	ds_read_b128 v[208:211], v242 offset:36864
	ds_read_b128 v[212:215], v242 offset:37888
	ds_read_b128 v[244:247], v242 offset:38912
	ds_read_b128 v[248:251], v242 offset:39936
	global_load_lds_dwordx4 v[216:217], off
	v_lshl_add_u64 v[216:217], s[34:35], 0, v[174:175]
	s_mov_b32 m0, s51
	s_nop 0
	global_load_lds_dwordx4 v[216:217], off
	s_waitcnt vmcnt(8)
	s_waitcnt lgkmcnt(0)
	s_setprio 1
	s_barrier
	v_mfma_f32_16x16x32_bf16 v[8:11], v[136:139], v[168:171], v[8:11]
	v_mfma_f32_16x16x32_bf16 v[128:131], v[144:147], v[168:171], v[128:131]
	v_mfma_f32_16x16x32_bf16 v[124:127], v[136:139], v[192:195], v[124:127]
	v_mfma_f32_16x16x32_bf16 v[120:123], v[144:147], v[192:195], v[120:123]
	v_mfma_f32_16x16x32_bf16 v[116:119], v[136:139], v[208:211], v[116:119]
	v_mfma_f32_16x16x32_bf16 v[112:115], v[144:147], v[208:211], v[112:115]
	v_mfma_f32_16x16x32_bf16 v[108:111], v[136:139], v[244:247], v[108:111]
	v_mfma_f32_16x16x32_bf16 v[104:107], v[144:147], v[244:247], v[104:107]
	v_mfma_f32_16x16x32_bf16 v[8:11], v[140:143], v[188:191], v[8:11]
	v_mfma_f32_16x16x32_bf16 v[128:131], v[148:151], v[188:191], v[128:131]
	v_mfma_f32_16x16x32_bf16 v[124:127], v[140:143], v[204:207], v[124:127]
	v_mfma_f32_16x16x32_bf16 v[120:123], v[148:151], v[204:207], v[120:123]
	v_mfma_f32_16x16x32_bf16 v[116:119], v[140:143], v[212:215], v[116:119]
	v_mfma_f32_16x16x32_bf16 v[112:115], v[148:151], v[212:215], v[112:115]
	v_mfma_f32_16x16x32_bf16 v[108:111], v[140:143], v[248:251], v[108:111]
	v_mfma_f32_16x16x32_bf16 v[104:107], v[148:151], v[248:251], v[104:107]
	s_setprio 0
	s_setprio 1
	v_mfma_f32_16x16x32_bf16 v[100:103], v[152:155], v[168:171], v[100:103]
	v_mfma_f32_16x16x32_bf16 v[96:99], v[160:163], v[168:171], v[96:99]
	v_mfma_f32_16x16x32_bf16 v[92:95], v[152:155], v[192:195], v[92:95]
	v_mfma_f32_16x16x32_bf16 v[88:91], v[160:163], v[192:195], v[88:91]
	v_mfma_f32_16x16x32_bf16 v[84:87], v[152:155], v[208:211], v[84:87]
	v_mfma_f32_16x16x32_bf16 v[80:83], v[160:163], v[208:211], v[80:83]
	v_mfma_f32_16x16x32_bf16 v[76:79], v[152:155], v[244:247], v[76:79]
	v_mfma_f32_16x16x32_bf16 v[72:75], v[160:163], v[244:247], v[72:75]
	v_mfma_f32_16x16x32_bf16 v[100:103], v[156:159], v[188:191], v[100:103]
	v_mfma_f32_16x16x32_bf16 v[96:99], v[164:167], v[188:191], v[96:99]
	v_mfma_f32_16x16x32_bf16 v[92:95], v[156:159], v[204:207], v[92:95]
	v_mfma_f32_16x16x32_bf16 v[88:91], v[164:167], v[204:207], v[88:91]
	v_mfma_f32_16x16x32_bf16 v[84:87], v[156:159], v[212:215], v[84:87]
	v_mfma_f32_16x16x32_bf16 v[80:83], v[164:167], v[212:215], v[80:83]
	v_mfma_f32_16x16x32_bf16 v[76:79], v[156:159], v[248:251], v[76:79]
	v_mfma_f32_16x16x32_bf16 v[72:75], v[164:167], v[248:251], v[72:75]
	s_setprio 0
	s_barrier
	s_add_i32 s34, s81, s38
	v_lshl_add_u64 v[196:197], v[196:197], 0, s[70:71]
	s_mov_b32 m0, s34
	ds_read_b128 v[168:171], v242 offset:49152
	ds_read_b128 v[188:191], v242 offset:50176
	ds_read_b128 v[192:195], v242 offset:51200
	ds_read_b128 v[204:207], v242 offset:52224
	ds_read_b128 v[208:211], v242 offset:53248
	ds_read_b128 v[212:215], v242 offset:54272
	ds_read_b128 v[244:247], v242 offset:55296
	ds_read_b128 v[248:251], v242 offset:56320
	global_load_lds_dwordx4 v[196:197], off
	s_add_i32 m0, s34, 0x2000
	s_add_u32 s12, s12, 0x80080
	v_lshl_add_u64 v[196:197], v[198:199], 0, s[70:71]
	s_addc_u32 s13, s13, 0
	s_add_i32 s34, s83, s38
	global_load_lds_dwordx4 v[196:197], off
	v_lshl_add_u64 v[196:197], s[12:13], 0, v[172:173]
	s_mov_b32 m0, s34
	s_nop 0
	global_load_lds_dwordx4 v[196:197], off
	v_lshl_add_u64 v[196:197], s[12:13], 0, v[176:177]
	s_add_i32 m0, s34, 0x2000
	s_nop 0
	global_load_lds_dwordx4 v[196:197], off
	v_lshl_add_u64 v[196:197], v[200:201], 0, s[70:71]
	s_mov_b32 m0, s74
	s_nop 0
	global_load_lds_dwordx4 v[196:197], off
	v_lshl_add_u64 v[196:197], v[202:203], 0, s[70:71]
	s_mov_b32 m0, s75
	s_nop 0
	global_load_lds_dwordx4 v[196:197], off
	s_waitcnt vmcnt(8)
	s_waitcnt lgkmcnt(0)
	s_setprio 1
	s_barrier
	v_mfma_f32_16x16x32_bf16 v[68:71], v[136:139], v[168:171], v[68:71]
	v_mfma_f32_16x16x32_bf16 v[64:67], v[144:147], v[168:171], v[64:67]
	v_mfma_f32_16x16x32_bf16 v[60:63], v[136:139], v[192:195], v[60:63]
	v_mfma_f32_16x16x32_bf16 v[56:59], v[144:147], v[192:195], v[56:59]
	v_mfma_f32_16x16x32_bf16 v[52:55], v[136:139], v[208:211], v[52:55]
	v_mfma_f32_16x16x32_bf16 v[48:51], v[144:147], v[208:211], v[48:51]
	v_mfma_f32_16x16x32_bf16 v[44:47], v[136:139], v[244:247], v[44:47]
	v_mfma_f32_16x16x32_bf16 v[40:43], v[144:147], v[244:247], v[40:43]
	v_mfma_f32_16x16x32_bf16 v[68:71], v[140:143], v[188:191], v[68:71]
	v_mfma_f32_16x16x32_bf16 v[64:67], v[148:151], v[188:191], v[64:67]
	v_mfma_f32_16x16x32_bf16 v[60:63], v[140:143], v[204:207], v[60:63]
	v_mfma_f32_16x16x32_bf16 v[56:59], v[148:151], v[204:207], v[56:59]
	v_mfma_f32_16x16x32_bf16 v[52:55], v[140:143], v[212:215], v[52:55]
	v_mfma_f32_16x16x32_bf16 v[48:51], v[148:151], v[212:215], v[48:51]
	v_mfma_f32_16x16x32_bf16 v[44:47], v[140:143], v[248:251], v[44:47]
	v_mfma_f32_16x16x32_bf16 v[40:43], v[148:151], v[248:251], v[40:43]
	s_setprio 0
	s_setprio 1
	v_mfma_f32_16x16x32_bf16 v[36:39], v[152:155], v[168:171], v[36:39]
	v_mfma_f32_16x16x32_bf16 v[32:35], v[160:163], v[168:171], v[32:35]
	v_mfma_f32_16x16x32_bf16 v[28:31], v[152:155], v[192:195], v[28:31]
	v_mfma_f32_16x16x32_bf16 v[24:27], v[160:163], v[192:195], v[24:27]
	v_mfma_f32_16x16x32_bf16 v[20:23], v[152:155], v[208:211], v[20:23]
	v_mfma_f32_16x16x32_bf16 v[16:19], v[160:163], v[208:211], v[16:19]
	v_mfma_f32_16x16x32_bf16 v[12:15], v[152:155], v[244:247], v[12:15]
	v_mfma_f32_16x16x32_bf16 v[4:7], v[160:163], v[244:247], v[4:7]
	v_mfma_f32_16x16x32_bf16 v[36:39], v[156:159], v[188:191], v[36:39]
	v_mfma_f32_16x16x32_bf16 v[32:35], v[164:167], v[188:191], v[32:35]
	v_mfma_f32_16x16x32_bf16 v[28:31], v[156:159], v[204:207], v[28:31]
	v_mfma_f32_16x16x32_bf16 v[24:27], v[164:167], v[204:207], v[24:27]
	v_mfma_f32_16x16x32_bf16 v[20:23], v[156:159], v[212:215], v[20:23]
	v_mfma_f32_16x16x32_bf16 v[16:19], v[164:167], v[212:215], v[16:19]
	v_mfma_f32_16x16x32_bf16 v[12:15], v[156:159], v[248:251], v[12:15]
	v_mfma_f32_16x16x32_bf16 v[4:7], v[164:167], v[248:251], v[4:7]
	s_setprio 0
	s_barrier
	s_add_i32 s42, s42, 2
	s_add_u32 s8, s8, 0x100
	s_addc_u32 s9, s9, 0
	s_cmp_gt_u32 s42, 29
	s_cbranch_scc0 .LBB0_180
	s_and_b64 vcc, exec, s[20:21]
	s_cbranch_vccz .LBB0_183
	s_barrier

.LBB0_319:
	s_add_u32 s12, s28, s8
	s_addc_u32 s13, s29, s9
	s_add_u32 s12, s12, 0x100
	s_addc_u32 s13, s13, 0
	s_add_u32 s43, s92, s8
	s_addc_u32 s66, s93, s9
	s_add_i32 s67, 0, 0x10000
	s_cmpk_eq_i32 s8, 0xf00
	s_cselect_b32 s17, s27, s13
	s_cselect_b32 s16, s36, s12
	s_cselect_b32 s13, s25, s66
	s_cselect_b32 s12, s37, s43
	s_add_i32 s43, 0, 0x14000
	v_add_u32_e32 v148, s67, v229
	v_add_u32_e32 v164, s43, v229
	ds_read_b128 v[136:139], v148
	ds_read_b128 v[140:143], v148 offset:1024
	ds_read_b128 v[144:147], v148 offset:2048
	ds_read_b128 v[148:151], v148 offset:3072
	ds_read_b128 v[152:155], v164
	ds_read_b128 v[156:159], v164 offset:1024
	ds_read_b128 v[160:163], v164 offset:2048
	ds_read_b128 v[164:167], v164 offset:3072
	v_lshl_add_u64 v[194:195], v[132:133], 0, s[8:9]
	s_add_i32 m0, s39, 0xc000
	ds_read_b128 v[168:171], v242
	ds_read_b128 v[186:189], v242 offset:1024
	ds_read_b128 v[190:193], v242 offset:2048
	ds_read_b128 v[204:207], v242 offset:3072
	ds_read_b128 v[208:211], v242 offset:4096
	ds_read_b128 v[212:215], v242 offset:5120
	ds_read_b128 v[244:247], v242 offset:6144
	ds_read_b128 v[248:251], v242 offset:7168
	global_load_lds_dwordx4 v[194:195], off
	v_lshl_add_u64 v[194:195], v[134:135], 0, s[8:9]
	s_add_i32 m0, s39, 0xe000
	s_nop 0
	global_load_lds_dwordx4 v[194:195], off
	s_waitcnt vmcnt(8)
	s_waitcnt lgkmcnt(0)
	s_setprio 1
	s_barrier
	v_mfma_f32_16x16x32_bf16 v[8:11], v[136:139], v[168:171], v[8:11]
	v_mfma_f32_16x16x32_bf16 v[128:131], v[144:147], v[168:171], v[128:131]
	v_mfma_f32_16x16x32_bf16 v[124:127], v[136:139], v[190:193], v[124:127]
	v_mfma_f32_16x16x32_bf16 v[120:123], v[144:147], v[190:193], v[120:123]
	v_mfma_f32_16x16x32_bf16 v[116:119], v[136:139], v[208:211], v[116:119]
	v_mfma_f32_16x16x32_bf16 v[112:115], v[144:147], v[208:211], v[112:115]
	v_mfma_f32_16x16x32_bf16 v[108:111], v[136:139], v[244:247], v[108:111]
	v_mfma_f32_16x16x32_bf16 v[104:107], v[144:147], v[244:247], v[104:107]
	v_mfma_f32_16x16x32_bf16 v[8:11], v[140:143], v[186:189], v[8:11]
	v_mfma_f32_16x16x32_bf16 v[128:131], v[148:151], v[186:189], v[128:131]
	v_mfma_f32_16x16x32_bf16 v[124:127], v[140:143], v[204:207], v[124:127]
	v_mfma_f32_16x16x32_bf16 v[120:123], v[148:151], v[204:207], v[120:123]
	v_mfma_f32_16x16x32_bf16 v[116:119], v[140:143], v[212:215], v[116:119]
	v_mfma_f32_16x16x32_bf16 v[112:115], v[148:151], v[212:215], v[112:115]
	v_mfma_f32_16x16x32_bf16 v[108:111], v[140:143], v[248:251], v[108:111]
	v_mfma_f32_16x16x32_bf16 v[104:107], v[148:151], v[248:251], v[104:107]
	s_setprio 0
	s_setprio 1
	v_mfma_f32_16x16x32_bf16 v[100:103], v[152:155], v[168:171], v[100:103]
	v_mfma_f32_16x16x32_bf16 v[96:99], v[160:163], v[168:171], v[96:99]
	v_mfma_f32_16x16x32_bf16 v[92:95], v[152:155], v[190:193], v[92:95]
	v_mfma_f32_16x16x32_bf16 v[88:91], v[160:163], v[190:193], v[88:91]
	v_mfma_f32_16x16x32_bf16 v[84:87], v[152:155], v[208:211], v[84:87]
	v_mfma_f32_16x16x32_bf16 v[80:83], v[160:163], v[208:211], v[80:83]
	v_mfma_f32_16x16x32_bf16 v[76:79], v[152:155], v[244:247], v[76:79]
	v_mfma_f32_16x16x32_bf16 v[72:75], v[160:163], v[244:247], v[72:75]
	v_mfma_f32_16x16x32_bf16 v[100:103], v[156:159], v[186:189], v[100:103]
	v_mfma_f32_16x16x32_bf16 v[96:99], v[164:167], v[186:189], v[96:99]
	v_mfma_f32_16x16x32_bf16 v[92:95], v[156:159], v[204:207], v[92:95]
	v_mfma_f32_16x16x32_bf16 v[88:91], v[164:167], v[204:207], v[88:91]
	v_mfma_f32_16x16x32_bf16 v[84:87], v[156:159], v[212:215], v[84:87]
	v_mfma_f32_16x16x32_bf16 v[80:83], v[164:167], v[212:215], v[80:83]
	v_mfma_f32_16x16x32_bf16 v[76:79], v[156:159], v[248:251], v[76:79]
	v_mfma_f32_16x16x32_bf16 v[72:75], v[164:167], v[248:251], v[72:75]
	s_setprio 0
	s_barrier
	s_add_i32 s66, s67, s38
	v_lshl_add_u64 v[194:195], s[12:13], 0, v[172:173]
	s_mov_b32 m0, s66
	ds_read_b128 v[168:171], v242 offset:16384
	ds_read_b128 v[186:189], v242 offset:17408
	ds_read_b128 v[190:193], v242 offset:18432
	ds_read_b128 v[204:207], v242 offset:19456
	ds_read_b128 v[208:211], v242 offset:20480
	ds_read_b128 v[212:215], v242 offset:21504
	ds_read_b128 v[244:247], v242 offset:22528
	ds_read_b128 v[248:251], v242 offset:23552
	global_load_lds_dwordx4 v[194:195], off
	s_add_i32 m0, s66, 0x2000
	s_add_u32 s66, s12, 0x80000
	v_lshl_add_u64 v[196:197], s[12:13], 0, v[176:177]
	s_addc_u32 s67, s13, 0
	s_add_i32 s43, s43, s38
	global_load_lds_dwordx4 v[196:197], off
	v_lshl_add_u64 v[198:199], s[66:67], 0, v[172:173]
	s_mov_b32 m0, s43
	v_lshl_add_u64 v[200:201], s[16:17], 0, v[174:175]
	global_load_lds_dwordx4 v[198:199], off
	v_lshl_add_u64 v[198:199], s[66:67], 0, v[176:177]
	s_add_i32 m0, s43, 0x2000
	s_nop 0
	global_load_lds_dwordx4 v[198:199], off
	v_lshl_add_u64 v[198:199], s[16:17], 0, v[0:1]
	s_mov_b32 m0, s39
	s_nop 0
	global_load_lds_dwordx4 v[198:199], off
	s_mov_b32 m0, s46
	s_nop 0
	global_load_lds_dwordx4 v[200:201], off
	s_waitcnt vmcnt(8)
	s_waitcnt lgkmcnt(0)
	s_setprio 1
	s_barrier
	v_mfma_f32_16x16x32_bf16 v[68:71], v[136:139], v[168:171], v[68:71]
	v_mfma_f32_16x16x32_bf16 v[64:67], v[144:147], v[168:171], v[64:67]
	v_mfma_f32_16x16x32_bf16 v[60:63], v[136:139], v[190:193], v[60:63]
	v_mfma_f32_16x16x32_bf16 v[56:59], v[144:147], v[190:193], v[56:59]
	v_mfma_f32_16x16x32_bf16 v[52:55], v[136:139], v[208:211], v[52:55]
	v_mfma_f32_16x16x32_bf16 v[48:51], v[144:147], v[208:211], v[48:51]
	v_mfma_f32_16x16x32_bf16 v[44:47], v[136:139], v[244:247], v[44:47]
	v_mfma_f32_16x16x32_bf16 v[40:43], v[144:147], v[244:247], v[40:43]
	v_mfma_f32_16x16x32_bf16 v[68:71], v[140:143], v[186:189], v[68:71]
	v_mfma_f32_16x16x32_bf16 v[64:67], v[148:151], v[186:189], v[64:67]
	v_mfma_f32_16x16x32_bf16 v[60:63], v[140:143], v[204:207], v[60:63]
	v_mfma_f32_16x16x32_bf16 v[56:59], v[148:151], v[204:207], v[56:59]
	v_mfma_f32_16x16x32_bf16 v[52:55], v[140:143], v[212:215], v[52:55]
	v_mfma_f32_16x16x32_bf16 v[48:51], v[148:151], v[212:215], v[48:51]
	v_mfma_f32_16x16x32_bf16 v[44:47], v[140:143], v[248:251], v[44:47]
	v_mfma_f32_16x16x32_bf16 v[40:43], v[148:151], v[248:251], v[40:43]
	s_setprio 0
	s_setprio 1
	v_mfma_f32_16x16x32_bf16 v[36:39], v[152:155], v[168:171], v[36:39]
	v_mfma_f32_16x16x32_bf16 v[32:35], v[160:163], v[168:171], v[32:35]
	v_mfma_f32_16x16x32_bf16 v[28:31], v[152:155], v[190:193], v[28:31]
	v_mfma_f32_16x16x32_bf16 v[24:27], v[160:163], v[190:193], v[24:27]
	v_mfma_f32_16x16x32_bf16 v[20:23], v[152:155], v[208:211], v[20:23]
	v_mfma_f32_16x16x32_bf16 v[16:19], v[160:163], v[208:211], v[16:19]
	v_mfma_f32_16x16x32_bf16 v[12:15], v[152:155], v[244:247], v[12:15]
	v_mfma_f32_16x16x32_bf16 v[4:7], v[160:163], v[244:247], v[4:7]
	v_mfma_f32_16x16x32_bf16 v[36:39], v[156:159], v[186:189], v[36:39]
	v_mfma_f32_16x16x32_bf16 v[32:35], v[164:167], v[186:189], v[32:35]
	v_mfma_f32_16x16x32_bf16 v[28:31], v[156:159], v[204:207], v[28:31]
	v_mfma_f32_16x16x32_bf16 v[24:27], v[164:167], v[204:207], v[24:27]
	v_mfma_f32_16x16x32_bf16 v[20:23], v[156:159], v[212:215], v[20:23]
	v_mfma_f32_16x16x32_bf16 v[16:19], v[164:167], v[212:215], v[16:19]
	v_mfma_f32_16x16x32_bf16 v[12:15], v[156:159], v[248:251], v[12:15]
	v_mfma_f32_16x16x32_bf16 v[4:7], v[164:167], v[248:251], v[4:7]
	s_setprio 0
	s_barrier
	s_add_i32 s43, 0, 0x18000
	s_add_i32 s66, 0, 0x1c000
	v_add_u32_e32 v148, s43, v229
	v_add_u32_e32 v164, s66, v229
	ds_read_b128 v[136:139], v148
	ds_read_b128 v[140:143], v148 offset:1024
	ds_read_b128 v[144:147], v148 offset:2048
	ds_read_b128 v[148:151], v148 offset:3072
	ds_read_b128 v[152:155], v164
	ds_read_b128 v[156:159], v164 offset:1024
	ds_read_b128 v[160:163], v164 offset:2048
	ds_read_b128 v[164:167], v164 offset:3072
	s_add_u32 s16, s16, 0x80000
	s_addc_u32 s17, s17, 0
	s_mov_b32 m0, s47
	v_lshl_add_u64 v[202:203], s[16:17], 0, v[0:1]
	ds_read_b128 v[168:171], v242 offset:32768
	ds_read_b128 v[186:189], v242 offset:33792
	ds_read_b128 v[190:193], v242 offset:34816
	ds_read_b128 v[204:207], v242 offset:35840
	ds_read_b128 v[208:211], v242 offset:36864
	ds_read_b128 v[212:215], v242 offset:37888
	ds_read_b128 v[244:247], v242 offset:38912
	ds_read_b128 v[248:251], v242 offset:39936
	global_load_lds_dwordx4 v[202:203], off
	v_lshl_add_u64 v[202:203], s[16:17], 0, v[174:175]
	s_mov_b32 m0, s51
	s_nop 0
	global_load_lds_dwordx4 v[202:203], off
	s_waitcnt vmcnt(8)
	s_waitcnt lgkmcnt(0)
	s_setprio 1
	s_barrier
	v_mfma_f32_16x16x32_bf16 v[8:11], v[136:139], v[168:171], v[8:11]
	v_mfma_f32_16x16x32_bf16 v[128:131], v[144:147], v[168:171], v[128:131]
	v_mfma_f32_16x16x32_bf16 v[124:127], v[136:139], v[190:193], v[124:127]
	v_mfma_f32_16x16x32_bf16 v[120:123], v[144:147], v[190:193], v[120:123]
	v_mfma_f32_16x16x32_bf16 v[116:119], v[136:139], v[208:211], v[116:119]
	v_mfma_f32_16x16x32_bf16 v[112:115], v[144:147], v[208:211], v[112:115]
	v_mfma_f32_16x16x32_bf16 v[108:111], v[136:139], v[244:247], v[108:111]
	v_mfma_f32_16x16x32_bf16 v[104:107], v[144:147], v[244:247], v[104:107]
	v_mfma_f32_16x16x32_bf16 v[8:11], v[140:143], v[186:189], v[8:11]
	v_mfma_f32_16x16x32_bf16 v[128:131], v[148:151], v[186:189], v[128:131]
	v_mfma_f32_16x16x32_bf16 v[124:127], v[140:143], v[204:207], v[124:127]
	v_mfma_f32_16x16x32_bf16 v[120:123], v[148:151], v[204:207], v[120:123]
	v_mfma_f32_16x16x32_bf16 v[116:119], v[140:143], v[212:215], v[116:119]
	v_mfma_f32_16x16x32_bf16 v[112:115], v[148:151], v[212:215], v[112:115]
	v_mfma_f32_16x16x32_bf16 v[108:111], v[140:143], v[248:251], v[108:111]
	v_mfma_f32_16x16x32_bf16 v[104:107], v[148:151], v[248:251], v[104:107]
	s_setprio 0
	s_setprio 1
	v_mfma_f32_16x16x32_bf16 v[100:103], v[152:155], v[168:171], v[100:103]
	v_mfma_f32_16x16x32_bf16 v[96:99], v[160:163], v[168:171], v[96:99]
	v_mfma_f32_16x16x32_bf16 v[92:95], v[152:155], v[190:193], v[92:95]
	v_mfma_f32_16x16x32_bf16 v[88:91], v[160:163], v[190:193], v[88:91]
	v_mfma_f32_16x16x32_bf16 v[84:87], v[152:155], v[208:211], v[84:87]
	v_mfma_f32_16x16x32_bf16 v[80:83], v[160:163], v[208:211], v[80:83]
	v_mfma_f32_16x16x32_bf16 v[76:79], v[152:155], v[244:247], v[76:79]
	v_mfma_f32_16x16x32_bf16 v[72:75], v[160:163], v[244:247], v[72:75]
	v_mfma_f32_16x16x32_bf16 v[100:103], v[156:159], v[186:189], v[100:103]
	v_mfma_f32_16x16x32_bf16 v[96:99], v[164:167], v[186:189], v[96:99]
	v_mfma_f32_16x16x32_bf16 v[92:95], v[156:159], v[204:207], v[92:95]
	v_mfma_f32_16x16x32_bf16 v[88:91], v[164:167], v[204:207], v[88:91]
	v_mfma_f32_16x16x32_bf16 v[84:87], v[156:159], v[212:215], v[84:87]
	v_mfma_f32_16x16x32_bf16 v[80:83], v[164:167], v[212:215], v[80:83]
	v_mfma_f32_16x16x32_bf16 v[76:79], v[156:159], v[248:251], v[76:79]
	v_mfma_f32_16x16x32_bf16 v[72:75], v[164:167], v[248:251], v[72:75]
	s_setprio 0
	s_barrier
	s_add_i32 s16, s43, s38
	v_lshl_add_u64 v[194:195], v[194:195], 0, s[70:71]
	s_mov_b32 m0, s16
	ds_read_b128 v[168:171], v242 offset:49152
	ds_read_b128 v[186:189], v242 offset:50176
	ds_read_b128 v[190:193], v242 offset:51200
	ds_read_b128 v[204:207], v242 offset:52224
	ds_read_b128 v[208:211], v242 offset:53248
	ds_read_b128 v[212:215], v242 offset:54272
	ds_read_b128 v[244:247], v242 offset:55296
	ds_read_b128 v[248:251], v242 offset:56320
	global_load_lds_dwordx4 v[194:195], off
	s_add_i32 m0, s16, 0x2000
	s_add_u32 s12, s12, 0x80080
	v_lshl_add_u64 v[194:195], v[196:197], 0, s[70:71]
	s_addc_u32 s13, s13, 0
	s_add_i32 s16, s66, s38
	global_load_lds_dwordx4 v[194:195], off
	v_lshl_add_u64 v[194:195], s[12:13], 0, v[172:173]
	s_mov_b32 m0, s16
	s_nop 0
	global_load_lds_dwordx4 v[194:195], off
	v_lshl_add_u64 v[194:195], s[12:13], 0, v[176:177]
	s_add_i32 m0, s16, 0x2000
	s_nop 0
	global_load_lds_dwordx4 v[194:195], off
	v_lshl_add_u64 v[194:195], v[198:199], 0, s[70:71]
	s_mov_b32 m0, s52
	s_nop 0
	global_load_lds_dwordx4 v[194:195], off
	v_lshl_add_u64 v[194:195], v[200:201], 0, s[70:71]
	s_mov_b32 m0, s54
	s_nop 0
	global_load_lds_dwordx4 v[194:195], off
	s_waitcnt vmcnt(8)
	s_waitcnt lgkmcnt(0)
	s_setprio 1
	s_barrier
	v_mfma_f32_16x16x32_bf16 v[68:71], v[136:139], v[168:171], v[68:71]
	v_mfma_f32_16x16x32_bf16 v[64:67], v[144:147], v[168:171], v[64:67]
	v_mfma_f32_16x16x32_bf16 v[60:63], v[136:139], v[190:193], v[60:63]
	v_mfma_f32_16x16x32_bf16 v[56:59], v[144:147], v[190:193], v[56:59]
	v_mfma_f32_16x16x32_bf16 v[52:55], v[136:139], v[208:211], v[52:55]
	v_mfma_f32_16x16x32_bf16 v[48:51], v[144:147], v[208:211], v[48:51]
	v_mfma_f32_16x16x32_bf16 v[44:47], v[136:139], v[244:247], v[44:47]
	v_mfma_f32_16x16x32_bf16 v[40:43], v[144:147], v[244:247], v[40:43]
	v_mfma_f32_16x16x32_bf16 v[68:71], v[140:143], v[186:189], v[68:71]
	v_mfma_f32_16x16x32_bf16 v[64:67], v[148:151], v[186:189], v[64:67]
	v_mfma_f32_16x16x32_bf16 v[60:63], v[140:143], v[204:207], v[60:63]
	v_mfma_f32_16x16x32_bf16 v[56:59], v[148:151], v[204:207], v[56:59]
	v_mfma_f32_16x16x32_bf16 v[52:55], v[140:143], v[212:215], v[52:55]
	v_mfma_f32_16x16x32_bf16 v[48:51], v[148:151], v[212:215], v[48:51]
	v_mfma_f32_16x16x32_bf16 v[44:47], v[140:143], v[248:251], v[44:47]
	v_mfma_f32_16x16x32_bf16 v[40:43], v[148:151], v[248:251], v[40:43]
	s_setprio 0
	s_setprio 1
	v_mfma_f32_16x16x32_bf16 v[36:39], v[152:155], v[168:171], v[36:39]
	v_mfma_f32_16x16x32_bf16 v[32:35], v[160:163], v[168:171], v[32:35]
	v_mfma_f32_16x16x32_bf16 v[28:31], v[152:155], v[190:193], v[28:31]
	v_mfma_f32_16x16x32_bf16 v[24:27], v[160:163], v[190:193], v[24:27]
	v_mfma_f32_16x16x32_bf16 v[20:23], v[152:155], v[208:211], v[20:23]
	v_mfma_f32_16x16x32_bf16 v[16:19], v[160:163], v[208:211], v[16:19]
	v_mfma_f32_16x16x32_bf16 v[12:15], v[152:155], v[244:247], v[12:15]
	v_mfma_f32_16x16x32_bf16 v[4:7], v[160:163], v[244:247], v[4:7]
	v_mfma_f32_16x16x32_bf16 v[36:39], v[156:159], v[186:189], v[36:39]
	v_mfma_f32_16x16x32_bf16 v[32:35], v[164:167], v[186:189], v[32:35]
	v_mfma_f32_16x16x32_bf16 v[28:31], v[156:159], v[204:207], v[28:31]
	v_mfma_f32_16x16x32_bf16 v[24:27], v[164:167], v[204:207], v[24:27]
	v_mfma_f32_16x16x32_bf16 v[20:23], v[156:159], v[212:215], v[20:23]
	v_mfma_f32_16x16x32_bf16 v[16:19], v[164:167], v[212:215], v[16:19]
	v_mfma_f32_16x16x32_bf16 v[12:15], v[156:159], v[248:251], v[12:15]
	v_mfma_f32_16x16x32_bf16 v[4:7], v[164:167], v[248:251], v[4:7]
	s_setprio 0
	s_barrier
	s_add_i32 s42, s42, 2
	s_add_u32 s8, s8, 0x100
	s_addc_u32 s9, s9, 0
	s_cmp_gt_u32 s42, 29
	s_cbranch_scc0 .LBB0_319
	s_and_b64 vcc, exec, s[22:23]
	s_cbranch_vccz .LBB0_322
	s_barrier

.LBB0_803:
	s_add_u32 s12, s28, s8
	s_addc_u32 s13, s29, s9
	s_add_u32 s12, s12, 0x100
	s_addc_u32 s13, s13, 0
	s_add_u32 s81, s84, s8
	s_addc_u32 s83, s85, s9
	s_add_i32 s95, 0, 0x10000
	s_cmpk_eq_i32 s8, 0xf00
	s_cselect_b32 s37, s27, s13
	s_cselect_b32 s36, s42, s12
	s_cselect_b32 s13, s25, s83
	s_cselect_b32 s12, s43, s81
	s_add_i32 s81, 0, 0x14000
	v_add_u32_e32 v148, s95, v207
	v_add_u32_e32 v176, s81, v207
	ds_read_b128 v[136:139], v148
	ds_read_b128 v[140:143], v148 offset:1024
	ds_read_b128 v[144:147], v148 offset:2048
	ds_read_b128 v[148:151], v148 offset:3072
	ds_read_b128 v[152:155], v176
	ds_read_b128 v[156:159], v176 offset:1024
	ds_read_b128 v[160:163], v176 offset:2048
	s_waitcnt lgkmcnt(0)
	ds_read_b128 v[176:179], v176 offset:3072
	v_lshl_add_u64 v[196:197], v[132:133], 0, s[8:9]
	s_add_i32 m0, s75, 0xc000
	ds_read_b128 v[180:183], v209
	ds_read_b128 v[184:187], v209 offset:1024
	ds_read_b128 v[188:191], v209 offset:2048
	ds_read_b128 v[192:195], v209 offset:3072
	ds_read_b128 v[212:215], v209 offset:4096
	ds_read_b128 v[226:229], v209 offset:5120
	ds_read_b128 v[230:233], v209 offset:6144
	ds_read_b128 v[234:237], v209 offset:7168
	global_load_lds_dwordx4 v[196:197], off
	v_lshl_add_u64 v[196:197], v[134:135], 0, s[8:9]
	s_add_i32 m0, s75, 0xe000
	s_nop 0
	global_load_lds_dwordx4 v[196:197], off
	s_waitcnt vmcnt(8)
	s_waitcnt lgkmcnt(0)
	s_setprio 1
	s_barrier
	v_mfma_f32_16x16x32_bf16 v[8:11], v[136:139], v[180:183], v[8:11]
	v_mfma_f32_16x16x32_bf16 v[128:131], v[144:147], v[180:183], v[128:131]
	v_mfma_f32_16x16x32_bf16 v[124:127], v[136:139], v[188:191], v[124:127]
	v_mfma_f32_16x16x32_bf16 v[120:123], v[144:147], v[188:191], v[120:123]
	v_mfma_f32_16x16x32_bf16 v[116:119], v[136:139], v[212:215], v[116:119]
	v_mfma_f32_16x16x32_bf16 v[112:115], v[144:147], v[212:215], v[112:115]
	v_mfma_f32_16x16x32_bf16 v[108:111], v[136:139], v[230:233], v[108:111]
	v_mfma_f32_16x16x32_bf16 v[104:107], v[144:147], v[230:233], v[104:107]
	v_mfma_f32_16x16x32_bf16 v[8:11], v[140:143], v[184:187], v[8:11]
	v_mfma_f32_16x16x32_bf16 v[128:131], v[148:151], v[184:187], v[128:131]
	v_mfma_f32_16x16x32_bf16 v[124:127], v[140:143], v[192:195], v[124:127]
	v_mfma_f32_16x16x32_bf16 v[120:123], v[148:151], v[192:195], v[120:123]
	v_mfma_f32_16x16x32_bf16 v[116:119], v[140:143], v[226:229], v[116:119]
	v_mfma_f32_16x16x32_bf16 v[112:115], v[148:151], v[226:229], v[112:115]
	v_mfma_f32_16x16x32_bf16 v[108:111], v[140:143], v[234:237], v[108:111]
	v_mfma_f32_16x16x32_bf16 v[104:107], v[148:151], v[234:237], v[104:107]
	s_setprio 0
	s_setprio 1
	v_mfma_f32_16x16x32_bf16 v[100:103], v[152:155], v[180:183], v[100:103]
	v_mfma_f32_16x16x32_bf16 v[96:99], v[160:163], v[180:183], v[96:99]
	v_mfma_f32_16x16x32_bf16 v[92:95], v[152:155], v[188:191], v[92:95]
	v_mfma_f32_16x16x32_bf16 v[88:91], v[160:163], v[188:191], v[88:91]
	v_mfma_f32_16x16x32_bf16 v[84:87], v[152:155], v[212:215], v[84:87]
	v_mfma_f32_16x16x32_bf16 v[80:83], v[160:163], v[212:215], v[80:83]
	v_mfma_f32_16x16x32_bf16 v[76:79], v[152:155], v[230:233], v[76:79]
	v_mfma_f32_16x16x32_bf16 v[72:75], v[160:163], v[230:233], v[72:75]
	v_mfma_f32_16x16x32_bf16 v[100:103], v[156:159], v[184:187], v[100:103]
	v_mfma_f32_16x16x32_bf16 v[96:99], v[176:179], v[184:187], v[96:99]
	v_mfma_f32_16x16x32_bf16 v[92:95], v[156:159], v[192:195], v[92:95]
	v_mfma_f32_16x16x32_bf16 v[88:91], v[176:179], v[192:195], v[88:91]
	v_mfma_f32_16x16x32_bf16 v[84:87], v[156:159], v[226:229], v[84:87]
	v_mfma_f32_16x16x32_bf16 v[80:83], v[176:179], v[226:229], v[80:83]
	v_mfma_f32_16x16x32_bf16 v[76:79], v[156:159], v[234:237], v[76:79]
	v_mfma_f32_16x16x32_bf16 v[72:75], v[176:179], v[234:237], v[72:75]
	s_setprio 0
	s_barrier
	s_add_i32 s83, s95, s74
	v_lshl_add_u64 v[196:197], s[12:13], 0, v[164:165]
	s_mov_b32 m0, s83
	ds_read_b128 v[180:183], v209 offset:16384
	ds_read_b128 v[184:187], v209 offset:17408
	ds_read_b128 v[188:191], v209 offset:18432
	ds_read_b128 v[192:195], v209 offset:19456
	ds_read_b128 v[212:215], v209 offset:20480
	ds_read_b128 v[226:229], v209 offset:21504
	ds_read_b128 v[230:233], v209 offset:22528
	ds_read_b128 v[234:237], v209 offset:23552
	global_load_lds_dwordx4 v[196:197], off
	s_add_i32 m0, s83, 0x2000
	s_add_u32 vcc_lo, s12, 0x80000
	v_lshl_add_u64 v[198:199], s[12:13], 0, v[168:169]
	s_addc_u32 vcc_hi, s13, 0
	s_add_i32 s81, s81, s74
	global_load_lds_dwordx4 v[198:199], off
	v_lshl_add_u64 v[200:201], vcc, 0, v[164:165]
	s_mov_b32 m0, s81
	v_lshl_add_u64 v[202:203], s[36:37], 0, v[166:167]
	global_load_lds_dwordx4 v[200:201], off
	v_lshl_add_u64 v[200:201], vcc, 0, v[168:169]
	s_add_i32 m0, s81, 0x2000
	s_nop 0
	global_load_lds_dwordx4 v[200:201], off
	v_lshl_add_u64 v[200:201], s[36:37], 0, v[0:1]
	s_mov_b32 m0, s75
	s_nop 0
	global_load_lds_dwordx4 v[200:201], off
	s_mov_b32 m0, s15
	s_nop 0
	global_load_lds_dwordx4 v[202:203], off
	s_waitcnt vmcnt(8)
	s_waitcnt lgkmcnt(0)
	s_setprio 1
	s_barrier
	v_mfma_f32_16x16x32_bf16 v[68:71], v[136:139], v[180:183], v[68:71]
	v_mfma_f32_16x16x32_bf16 v[64:67], v[144:147], v[180:183], v[64:67]
	v_mfma_f32_16x16x32_bf16 v[60:63], v[136:139], v[188:191], v[60:63]
	v_mfma_f32_16x16x32_bf16 v[56:59], v[144:147], v[188:191], v[56:59]
	v_mfma_f32_16x16x32_bf16 v[52:55], v[136:139], v[212:215], v[52:55]
	v_mfma_f32_16x16x32_bf16 v[48:51], v[144:147], v[212:215], v[48:51]
	v_mfma_f32_16x16x32_bf16 v[44:47], v[136:139], v[230:233], v[44:47]
	v_mfma_f32_16x16x32_bf16 v[40:43], v[144:147], v[230:233], v[40:43]
	v_mfma_f32_16x16x32_bf16 v[68:71], v[140:143], v[184:187], v[68:71]
	v_mfma_f32_16x16x32_bf16 v[64:67], v[148:151], v[184:187], v[64:67]
	v_mfma_f32_16x16x32_bf16 v[60:63], v[140:143], v[192:195], v[60:63]
	v_mfma_f32_16x16x32_bf16 v[56:59], v[148:151], v[192:195], v[56:59]
	v_mfma_f32_16x16x32_bf16 v[52:55], v[140:143], v[226:229], v[52:55]
	v_mfma_f32_16x16x32_bf16 v[48:51], v[148:151], v[226:229], v[48:51]
	v_mfma_f32_16x16x32_bf16 v[44:47], v[140:143], v[234:237], v[44:47]
	v_mfma_f32_16x16x32_bf16 v[40:43], v[148:151], v[234:237], v[40:43]
	s_setprio 0
	s_setprio 1
	v_mfma_f32_16x16x32_bf16 v[36:39], v[152:155], v[180:183], v[36:39]
	v_mfma_f32_16x16x32_bf16 v[32:35], v[160:163], v[180:183], v[32:35]
	v_mfma_f32_16x16x32_bf16 v[28:31], v[152:155], v[188:191], v[28:31]
	v_mfma_f32_16x16x32_bf16 v[24:27], v[160:163], v[188:191], v[24:27]
	v_mfma_f32_16x16x32_bf16 v[20:23], v[152:155], v[212:215], v[20:23]
	v_mfma_f32_16x16x32_bf16 v[16:19], v[160:163], v[212:215], v[16:19]
	v_mfma_f32_16x16x32_bf16 v[12:15], v[152:155], v[230:233], v[12:15]
	v_mfma_f32_16x16x32_bf16 v[4:7], v[160:163], v[230:233], v[4:7]
	v_mfma_f32_16x16x32_bf16 v[36:39], v[156:159], v[184:187], v[36:39]
	v_mfma_f32_16x16x32_bf16 v[32:35], v[176:179], v[184:187], v[32:35]
	v_mfma_f32_16x16x32_bf16 v[28:31], v[156:159], v[192:195], v[28:31]
	v_mfma_f32_16x16x32_bf16 v[24:27], v[176:179], v[192:195], v[24:27]
	v_mfma_f32_16x16x32_bf16 v[20:23], v[156:159], v[226:229], v[20:23]
	v_mfma_f32_16x16x32_bf16 v[16:19], v[176:179], v[226:229], v[16:19]
	v_mfma_f32_16x16x32_bf16 v[12:15], v[156:159], v[234:237], v[12:15]
	v_mfma_f32_16x16x32_bf16 v[4:7], v[176:179], v[234:237], v[4:7]
	s_setprio 0
	s_barrier
	s_add_i32 s81, 0, 0x18000
	s_add_i32 s83, 0, 0x1c000
	v_add_u32_e32 v148, s81, v207
	v_add_u32_e32 v176, s83, v207
	ds_read_b128 v[136:139], v148
	ds_read_b128 v[140:143], v148 offset:1024
	ds_read_b128 v[144:147], v148 offset:2048
	ds_read_b128 v[148:151], v148 offset:3072
	ds_read_b128 v[152:155], v176
	ds_read_b128 v[156:159], v176 offset:1024
	ds_read_b128 v[160:163], v176 offset:2048
	ds_read_b128 v[176:179], v176 offset:3072
	s_add_u32 s36, s36, 0x80000
	s_addc_u32 s37, s37, 0
	s_mov_b32 m0, s38
	v_lshl_add_u64 v[216:217], s[36:37], 0, v[0:1]
	ds_read_b128 v[180:183], v209 offset:32768
	ds_read_b128 v[184:187], v209 offset:33792
	ds_read_b128 v[188:191], v209 offset:34816
	ds_read_b128 v[192:195], v209 offset:35840
	ds_read_b128 v[212:215], v209 offset:36864
	ds_read_b128 v[226:229], v209 offset:37888
	ds_read_b128 v[230:233], v209 offset:38912
	ds_read_b128 v[234:237], v209 offset:39936
	global_load_lds_dwordx4 v[216:217], off
	v_lshl_add_u64 v[216:217], s[36:37], 0, v[166:167]
	s_mov_b32 m0, s39
	s_nop 0
	global_load_lds_dwordx4 v[216:217], off
	s_waitcnt vmcnt(8)
	s_waitcnt lgkmcnt(0)
	s_setprio 1
	s_barrier
	v_mfma_f32_16x16x32_bf16 v[8:11], v[136:139], v[180:183], v[8:11]
	v_mfma_f32_16x16x32_bf16 v[128:131], v[144:147], v[180:183], v[128:131]
	v_mfma_f32_16x16x32_bf16 v[124:127], v[136:139], v[188:191], v[124:127]
	v_mfma_f32_16x16x32_bf16 v[120:123], v[144:147], v[188:191], v[120:123]
	v_mfma_f32_16x16x32_bf16 v[116:119], v[136:139], v[212:215], v[116:119]
	v_mfma_f32_16x16x32_bf16 v[112:115], v[144:147], v[212:215], v[112:115]
	v_mfma_f32_16x16x32_bf16 v[108:111], v[136:139], v[230:233], v[108:111]
	v_mfma_f32_16x16x32_bf16 v[104:107], v[144:147], v[230:233], v[104:107]
	v_mfma_f32_16x16x32_bf16 v[8:11], v[140:143], v[184:187], v[8:11]
	v_mfma_f32_16x16x32_bf16 v[128:131], v[148:151], v[184:187], v[128:131]
	v_mfma_f32_16x16x32_bf16 v[124:127], v[140:143], v[192:195], v[124:127]
	v_mfma_f32_16x16x32_bf16 v[120:123], v[148:151], v[192:195], v[120:123]
	v_mfma_f32_16x16x32_bf16 v[116:119], v[140:143], v[226:229], v[116:119]
	v_mfma_f32_16x16x32_bf16 v[112:115], v[148:151], v[226:229], v[112:115]
	v_mfma_f32_16x16x32_bf16 v[108:111], v[140:143], v[234:237], v[108:111]
	v_mfma_f32_16x16x32_bf16 v[104:107], v[148:151], v[234:237], v[104:107]
	s_setprio 0
	s_setprio 1
	v_mfma_f32_16x16x32_bf16 v[100:103], v[152:155], v[180:183], v[100:103]
	v_mfma_f32_16x16x32_bf16 v[96:99], v[160:163], v[180:183], v[96:99]
	v_mfma_f32_16x16x32_bf16 v[92:95], v[152:155], v[188:191], v[92:95]
	v_mfma_f32_16x16x32_bf16 v[88:91], v[160:163], v[188:191], v[88:91]
	v_mfma_f32_16x16x32_bf16 v[84:87], v[152:155], v[212:215], v[84:87]
	v_mfma_f32_16x16x32_bf16 v[80:83], v[160:163], v[212:215], v[80:83]
	v_mfma_f32_16x16x32_bf16 v[76:79], v[152:155], v[230:233], v[76:79]
	v_mfma_f32_16x16x32_bf16 v[72:75], v[160:163], v[230:233], v[72:75]
	v_mfma_f32_16x16x32_bf16 v[100:103], v[156:159], v[184:187], v[100:103]
	v_mfma_f32_16x16x32_bf16 v[96:99], v[176:179], v[184:187], v[96:99]
	v_mfma_f32_16x16x32_bf16 v[92:95], v[156:159], v[192:195], v[92:95]
	v_mfma_f32_16x16x32_bf16 v[88:91], v[176:179], v[192:195], v[88:91]
	v_mfma_f32_16x16x32_bf16 v[84:87], v[156:159], v[226:229], v[84:87]
	v_mfma_f32_16x16x32_bf16 v[80:83], v[176:179], v[226:229], v[80:83]
	v_mfma_f32_16x16x32_bf16 v[76:79], v[156:159], v[234:237], v[76:79]
	v_mfma_f32_16x16x32_bf16 v[72:75], v[176:179], v[234:237], v[72:75]
	s_setprio 0
	s_barrier
	s_add_i32 s36, s81, s74
	v_lshl_add_u64 v[196:197], v[196:197], 0, s[70:71]
	s_mov_b32 m0, s36
	ds_read_b128 v[180:183], v209 offset:49152
	ds_read_b128 v[184:187], v209 offset:50176
	ds_read_b128 v[188:191], v209 offset:51200
	ds_read_b128 v[192:195], v209 offset:52224
	ds_read_b128 v[212:215], v209 offset:53248
	ds_read_b128 v[226:229], v209 offset:54272
	ds_read_b128 v[230:233], v209 offset:55296
	ds_read_b128 v[234:237], v209 offset:56320
	global_load_lds_dwordx4 v[196:197], off
	s_add_i32 m0, s36, 0x2000
	s_add_u32 s12, s12, 0x80080
	v_lshl_add_u64 v[196:197], v[198:199], 0, s[70:71]
	s_addc_u32 s13, s13, 0
	s_add_i32 s36, s83, s74
	global_load_lds_dwordx4 v[196:197], off
	v_lshl_add_u64 v[196:197], s[12:13], 0, v[164:165]
	s_mov_b32 m0, s36
	s_nop 0
	global_load_lds_dwordx4 v[196:197], off
	v_lshl_add_u64 v[196:197], s[12:13], 0, v[168:169]
	s_add_i32 m0, s36, 0x2000
	s_nop 0
	global_load_lds_dwordx4 v[196:197], off
	v_lshl_add_u64 v[196:197], v[200:201], 0, s[70:71]
	s_mov_b32 m0, s51
	s_nop 0
	global_load_lds_dwordx4 v[196:197], off
	v_lshl_add_u64 v[196:197], v[202:203], 0, s[70:71]
	s_mov_b32 m0, s92
	s_nop 0
	global_load_lds_dwordx4 v[196:197], off
	s_waitcnt vmcnt(8)
	s_waitcnt lgkmcnt(0)
	s_setprio 1
	s_barrier
	v_mfma_f32_16x16x32_bf16 v[68:71], v[136:139], v[180:183], v[68:71]
	v_mfma_f32_16x16x32_bf16 v[64:67], v[144:147], v[180:183], v[64:67]
	v_mfma_f32_16x16x32_bf16 v[60:63], v[136:139], v[188:191], v[60:63]
	v_mfma_f32_16x16x32_bf16 v[56:59], v[144:147], v[188:191], v[56:59]
	v_mfma_f32_16x16x32_bf16 v[52:55], v[136:139], v[212:215], v[52:55]
	v_mfma_f32_16x16x32_bf16 v[48:51], v[144:147], v[212:215], v[48:51]
	v_mfma_f32_16x16x32_bf16 v[44:47], v[136:139], v[230:233], v[44:47]
	v_mfma_f32_16x16x32_bf16 v[40:43], v[144:147], v[230:233], v[40:43]
	v_mfma_f32_16x16x32_bf16 v[68:71], v[140:143], v[184:187], v[68:71]
	v_mfma_f32_16x16x32_bf16 v[64:67], v[148:151], v[184:187], v[64:67]
	v_mfma_f32_16x16x32_bf16 v[60:63], v[140:143], v[192:195], v[60:63]
	v_mfma_f32_16x16x32_bf16 v[56:59], v[148:151], v[192:195], v[56:59]
	v_mfma_f32_16x16x32_bf16 v[52:55], v[140:143], v[226:229], v[52:55]
	v_mfma_f32_16x16x32_bf16 v[48:51], v[148:151], v[226:229], v[48:51]
	v_mfma_f32_16x16x32_bf16 v[44:47], v[140:143], v[234:237], v[44:47]
	v_mfma_f32_16x16x32_bf16 v[40:43], v[148:151], v[234:237], v[40:43]
	s_setprio 0
	s_setprio 1
	v_mfma_f32_16x16x32_bf16 v[36:39], v[152:155], v[180:183], v[36:39]
	v_mfma_f32_16x16x32_bf16 v[32:35], v[160:163], v[180:183], v[32:35]
	v_mfma_f32_16x16x32_bf16 v[28:31], v[152:155], v[188:191], v[28:31]
	v_mfma_f32_16x16x32_bf16 v[24:27], v[160:163], v[188:191], v[24:27]
	v_mfma_f32_16x16x32_bf16 v[20:23], v[152:155], v[212:215], v[20:23]
	v_mfma_f32_16x16x32_bf16 v[16:19], v[160:163], v[212:215], v[16:19]
	v_mfma_f32_16x16x32_bf16 v[12:15], v[152:155], v[230:233], v[12:15]
	v_mfma_f32_16x16x32_bf16 v[4:7], v[160:163], v[230:233], v[4:7]
	v_mfma_f32_16x16x32_bf16 v[36:39], v[156:159], v[184:187], v[36:39]
	v_mfma_f32_16x16x32_bf16 v[32:35], v[176:179], v[184:187], v[32:35]
	v_mfma_f32_16x16x32_bf16 v[28:31], v[156:159], v[192:195], v[28:31]
	v_mfma_f32_16x16x32_bf16 v[24:27], v[176:179], v[192:195], v[24:27]
	v_mfma_f32_16x16x32_bf16 v[20:23], v[156:159], v[226:229], v[20:23]
	v_mfma_f32_16x16x32_bf16 v[16:19], v[176:179], v[226:229], v[16:19]
	v_mfma_f32_16x16x32_bf16 v[12:15], v[156:159], v[234:237], v[12:15]
	v_mfma_f32_16x16x32_bf16 v[4:7], v[176:179], v[234:237], v[4:7]
	s_setprio 0
	s_barrier
	s_add_i32 s52, s52, 2
	s_add_u32 s8, s8, 0x100
	s_addc_u32 s9, s9, 0
	s_cmp_gt_u32 s52, 29
	s_cbranch_scc0 .LBB0_803
	s_and_b64 vcc, exec, s[22:23]
	s_cbranch_vccz .LBB0_806
	s_barrier

.LBB0_975:
	s_add_u32 s34, s30, 0xfff80080
	s_addc_u32 s35, s31, -1
	s_add_i32 s81, 0, 0x10000
	s_cmp_eq_u32 s75, 28
	s_cselect_b32 s37, s25, s35
	s_cselect_b32 s36, s66, s34
	s_cselect_b32 s35, s23, s74
	s_cselect_b32 s34, s67, s69
	s_add_i32 s83, 0, 0x14000
	v_add_u32_e32 v144, s81, v182
	v_add_u32_e32 v170, s83, v182
	ds_read_b128 v[132:135], v144
	ds_read_b128 v[136:139], v144 offset:1024
	ds_read_b128 v[140:143], v144 offset:2048
	ds_read_b128 v[144:147], v144 offset:3072
	ds_read_b128 v[148:151], v170
	ds_read_b128 v[152:155], v170 offset:1024
	ds_read_b128 v[156:159], v170 offset:2048
	ds_read_b128 v[170:173], v170 offset:3072
	v_lshl_add_u64 v[212:213], s[30:31], 0, v[166:167]
	s_add_i32 m0, s15, 0xc000
	ds_read_b128 v[174:177], v186
	ds_read_b128 v[178:181], v186 offset:1024
	ds_read_b128 v[188:191], v186 offset:2048
	ds_read_b128 v[192:195], v186 offset:3072
	ds_read_b128 v[196:199], v186 offset:4096
	ds_read_b128 v[200:203], v186 offset:5120
	ds_read_b128 v[204:207], v186 offset:6144
	ds_read_b128 v[208:211], v186 offset:7168
	global_load_lds_dwordx4 v[212:213], off
	v_lshl_add_u64 v[212:213], s[30:31], 0, v[168:169]
	s_add_i32 m0, s15, 0xe000
	s_nop 0
	global_load_lds_dwordx4 v[212:213], off
	s_waitcnt vmcnt(8)
	s_waitcnt lgkmcnt(0)
	s_setprio 1
	s_barrier
	v_mfma_f32_16x16x32_bf16 v[128:131], v[132:135], v[174:177], v[128:131]
	v_mfma_f32_16x16x32_bf16 v[124:127], v[140:143], v[174:177], v[124:127]
	v_mfma_f32_16x16x32_bf16 v[112:115], v[132:135], v[188:191], v[112:115]
	v_mfma_f32_16x16x32_bf16 v[108:111], v[140:143], v[188:191], v[108:111]
	v_mfma_f32_16x16x32_bf16 v[96:99], v[132:135], v[196:199], v[96:99]
	v_mfma_f32_16x16x32_bf16 v[92:95], v[140:143], v[196:199], v[92:95]
	v_mfma_f32_16x16x32_bf16 v[80:83], v[132:135], v[204:207], v[80:83]
	v_mfma_f32_16x16x32_bf16 v[76:79], v[140:143], v[204:207], v[76:79]
	v_mfma_f32_16x16x32_bf16 v[128:131], v[136:139], v[178:181], v[128:131]
	v_mfma_f32_16x16x32_bf16 v[124:127], v[144:147], v[178:181], v[124:127]
	v_mfma_f32_16x16x32_bf16 v[112:115], v[136:139], v[192:195], v[112:115]
	v_mfma_f32_16x16x32_bf16 v[108:111], v[144:147], v[192:195], v[108:111]
	v_mfma_f32_16x16x32_bf16 v[96:99], v[136:139], v[200:203], v[96:99]
	v_mfma_f32_16x16x32_bf16 v[92:95], v[144:147], v[200:203], v[92:95]
	v_mfma_f32_16x16x32_bf16 v[80:83], v[136:139], v[208:211], v[80:83]
	v_mfma_f32_16x16x32_bf16 v[76:79], v[144:147], v[208:211], v[76:79]
	s_setprio 0
	s_setprio 1
	v_mfma_f32_16x16x32_bf16 v[120:123], v[148:151], v[174:177], v[120:123]
	v_mfma_f32_16x16x32_bf16 v[116:119], v[156:159], v[174:177], v[116:119]
	v_mfma_f32_16x16x32_bf16 v[104:107], v[148:151], v[188:191], v[104:107]
	v_mfma_f32_16x16x32_bf16 v[100:103], v[156:159], v[188:191], v[100:103]
	v_mfma_f32_16x16x32_bf16 v[88:91], v[148:151], v[196:199], v[88:91]
	v_mfma_f32_16x16x32_bf16 v[84:87], v[156:159], v[196:199], v[84:87]
	v_mfma_f32_16x16x32_bf16 v[72:75], v[148:151], v[204:207], v[72:75]
	v_mfma_f32_16x16x32_bf16 v[68:71], v[156:159], v[204:207], v[68:71]
	v_mfma_f32_16x16x32_bf16 v[120:123], v[152:155], v[178:181], v[120:123]
	v_mfma_f32_16x16x32_bf16 v[116:119], v[170:173], v[178:181], v[116:119]
	v_mfma_f32_16x16x32_bf16 v[104:107], v[152:155], v[192:195], v[104:107]
	v_mfma_f32_16x16x32_bf16 v[100:103], v[170:173], v[192:195], v[100:103]
	v_mfma_f32_16x16x32_bf16 v[88:91], v[152:155], v[200:203], v[88:91]
	v_mfma_f32_16x16x32_bf16 v[84:87], v[170:173], v[200:203], v[84:87]
	v_mfma_f32_16x16x32_bf16 v[72:75], v[152:155], v[208:211], v[72:75]
	v_mfma_f32_16x16x32_bf16 v[68:71], v[170:173], v[208:211], v[68:71]
	s_setprio 0
	s_barrier
	s_add_i32 s81, s81, s0
	v_lshl_add_u64 v[212:213], s[34:35], 0, v[162:163]
	s_mov_b32 m0, s81
	ds_read_b128 v[174:177], v186 offset:16384
	ds_read_b128 v[178:181], v186 offset:17408
	ds_read_b128 v[188:191], v186 offset:18432
	ds_read_b128 v[192:195], v186 offset:19456
	ds_read_b128 v[196:199], v186 offset:20480
	ds_read_b128 v[200:203], v186 offset:21504
	ds_read_b128 v[204:207], v186 offset:22528
	ds_read_b128 v[208:211], v186 offset:23552
	global_load_lds_dwordx4 v[212:213], off
	s_add_i32 m0, s81, 0x2000
	s_add_u32 s84, s34, 0x80000
	v_lshl_add_u64 v[214:215], s[34:35], 0, v[0:1]
	s_addc_u32 s85, s35, 0
	s_add_i32 s81, s83, s0
	global_load_lds_dwordx4 v[214:215], off
	v_lshl_add_u64 v[216:217], s[84:85], 0, v[162:163]
	s_mov_b32 m0, s81
	v_lshl_add_u64 v[226:227], s[36:37], 0, v[160:161]
	global_load_lds_dwordx4 v[216:217], off
	v_lshl_add_u64 v[216:217], s[84:85], 0, v[0:1]
	s_add_i32 m0, s81, 0x2000
	s_nop 0
	global_load_lds_dwordx4 v[216:217], off
	v_lshl_add_u64 v[216:217], s[36:37], 0, v[164:165]
	s_mov_b32 m0, s15
	s_nop 0
	global_load_lds_dwordx4 v[216:217], off
	s_mov_b32 m0, s38
	s_nop 0
	global_load_lds_dwordx4 v[226:227], off
	s_waitcnt vmcnt(8)
	s_waitcnt lgkmcnt(0)
	s_setprio 1
	s_barrier
	v_mfma_f32_16x16x32_bf16 v[64:67], v[132:135], v[174:177], v[64:67]
	v_mfma_f32_16x16x32_bf16 v[60:63], v[140:143], v[174:177], v[60:63]
	v_mfma_f32_16x16x32_bf16 v[48:51], v[132:135], v[188:191], v[48:51]
	v_mfma_f32_16x16x32_bf16 v[44:47], v[140:143], v[188:191], v[44:47]
	v_mfma_f32_16x16x32_bf16 v[32:35], v[132:135], v[196:199], v[32:35]
	v_mfma_f32_16x16x32_bf16 v[28:31], v[140:143], v[196:199], v[28:31]
	v_mfma_f32_16x16x32_bf16 v[16:19], v[132:135], v[204:207], v[16:19]
	v_mfma_f32_16x16x32_bf16 v[12:15], v[140:143], v[204:207], v[12:15]
	v_mfma_f32_16x16x32_bf16 v[64:67], v[136:139], v[178:181], v[64:67]
	v_mfma_f32_16x16x32_bf16 v[60:63], v[144:147], v[178:181], v[60:63]
	v_mfma_f32_16x16x32_bf16 v[48:51], v[136:139], v[192:195], v[48:51]
	v_mfma_f32_16x16x32_bf16 v[44:47], v[144:147], v[192:195], v[44:47]
	v_mfma_f32_16x16x32_bf16 v[32:35], v[136:139], v[200:203], v[32:35]
	v_mfma_f32_16x16x32_bf16 v[28:31], v[144:147], v[200:203], v[28:31]
	v_mfma_f32_16x16x32_bf16 v[16:19], v[136:139], v[208:211], v[16:19]
	v_mfma_f32_16x16x32_bf16 v[12:15], v[144:147], v[208:211], v[12:15]
	s_setprio 0
	s_setprio 1
	v_mfma_f32_16x16x32_bf16 v[56:59], v[148:151], v[174:177], v[56:59]
	v_mfma_f32_16x16x32_bf16 v[52:55], v[156:159], v[174:177], v[52:55]
	v_mfma_f32_16x16x32_bf16 v[40:43], v[148:151], v[188:191], v[40:43]
	v_mfma_f32_16x16x32_bf16 v[36:39], v[156:159], v[188:191], v[36:39]
	v_mfma_f32_16x16x32_bf16 v[24:27], v[148:151], v[196:199], v[24:27]
	v_mfma_f32_16x16x32_bf16 v[20:23], v[156:159], v[196:199], v[20:23]
	v_mfma_f32_16x16x32_bf16 v[8:11], v[148:151], v[204:207], v[8:11]
	v_mfma_f32_16x16x32_bf16 v[4:7], v[156:159], v[204:207], v[4:7]
	v_mfma_f32_16x16x32_bf16 v[56:59], v[152:155], v[178:181], v[56:59]
	v_mfma_f32_16x16x32_bf16 v[52:55], v[170:173], v[178:181], v[52:55]
	v_mfma_f32_16x16x32_bf16 v[40:43], v[152:155], v[192:195], v[40:43]
	v_mfma_f32_16x16x32_bf16 v[36:39], v[170:173], v[192:195], v[36:39]
	v_mfma_f32_16x16x32_bf16 v[24:27], v[152:155], v[200:203], v[24:27]
	v_mfma_f32_16x16x32_bf16 v[20:23], v[170:173], v[200:203], v[20:23]
	v_mfma_f32_16x16x32_bf16 v[8:11], v[152:155], v[208:211], v[8:11]
	v_mfma_f32_16x16x32_bf16 v[4:7], v[170:173], v[208:211], v[4:7]
	s_setprio 0
	s_barrier
	s_add_i32 s81, 0, 0x18000
	s_add_i32 s83, 0, 0x1c000
	v_add_u32_e32 v144, s81, v182
	v_add_u32_e32 v170, s83, v182
	ds_read_b128 v[132:135], v144
	ds_read_b128 v[136:139], v144 offset:1024
	ds_read_b128 v[140:143], v144 offset:2048
	ds_read_b128 v[144:147], v144 offset:3072
	ds_read_b128 v[148:151], v170
	ds_read_b128 v[152:155], v170 offset:1024
	ds_read_b128 v[156:159], v170 offset:2048
	ds_read_b128 v[170:173], v170 offset:3072
	s_add_u32 s36, s36, 0x80000
	s_addc_u32 s37, s37, 0
	s_mov_b32 m0, s39
	v_lshl_add_u64 v[228:229], s[36:37], 0, v[164:165]
	ds_read_b128 v[174:177], v186 offset:32768
	ds_read_b128 v[178:181], v186 offset:33792
	ds_read_b128 v[188:191], v186 offset:34816
	ds_read_b128 v[192:195], v186 offset:35840
	ds_read_b128 v[196:199], v186 offset:36864
	ds_read_b128 v[200:203], v186 offset:37888
	ds_read_b128 v[204:207], v186 offset:38912
	ds_read_b128 v[208:211], v186 offset:39936
	global_load_lds_dwordx4 v[228:229], off
	v_lshl_add_u64 v[228:229], s[36:37], 0, v[160:161]
	s_mov_b32 m0, s43
	s_nop 0
	global_load_lds_dwordx4 v[228:229], off
	s_waitcnt vmcnt(8)
	s_waitcnt lgkmcnt(0)
	s_setprio 1
	s_barrier
	v_mfma_f32_16x16x32_bf16 v[128:131], v[132:135], v[174:177], v[128:131]
	v_mfma_f32_16x16x32_bf16 v[124:127], v[140:143], v[174:177], v[124:127]
	v_mfma_f32_16x16x32_bf16 v[112:115], v[132:135], v[188:191], v[112:115]
	v_mfma_f32_16x16x32_bf16 v[108:111], v[140:143], v[188:191], v[108:111]
	v_mfma_f32_16x16x32_bf16 v[96:99], v[132:135], v[196:199], v[96:99]
	v_mfma_f32_16x16x32_bf16 v[92:95], v[140:143], v[196:199], v[92:95]
	v_mfma_f32_16x16x32_bf16 v[80:83], v[132:135], v[204:207], v[80:83]
	v_mfma_f32_16x16x32_bf16 v[76:79], v[140:143], v[204:207], v[76:79]
	v_mfma_f32_16x16x32_bf16 v[128:131], v[136:139], v[178:181], v[128:131]
	v_mfma_f32_16x16x32_bf16 v[124:127], v[144:147], v[178:181], v[124:127]
	v_mfma_f32_16x16x32_bf16 v[112:115], v[136:139], v[192:195], v[112:115]
	v_mfma_f32_16x16x32_bf16 v[108:111], v[144:147], v[192:195], v[108:111]
	v_mfma_f32_16x16x32_bf16 v[96:99], v[136:139], v[200:203], v[96:99]
	v_mfma_f32_16x16x32_bf16 v[92:95], v[144:147], v[200:203], v[92:95]
	v_mfma_f32_16x16x32_bf16 v[80:83], v[136:139], v[208:211], v[80:83]
	v_mfma_f32_16x16x32_bf16 v[76:79], v[144:147], v[208:211], v[76:79]
	s_setprio 0
	s_setprio 1
	v_mfma_f32_16x16x32_bf16 v[120:123], v[148:151], v[174:177], v[120:123]
	v_mfma_f32_16x16x32_bf16 v[116:119], v[156:159], v[174:177], v[116:119]
	v_mfma_f32_16x16x32_bf16 v[104:107], v[148:151], v[188:191], v[104:107]
	v_mfma_f32_16x16x32_bf16 v[100:103], v[156:159], v[188:191], v[100:103]
	v_mfma_f32_16x16x32_bf16 v[88:91], v[148:151], v[196:199], v[88:91]
	v_mfma_f32_16x16x32_bf16 v[84:87], v[156:159], v[196:199], v[84:87]
	v_mfma_f32_16x16x32_bf16 v[72:75], v[148:151], v[204:207], v[72:75]
	v_mfma_f32_16x16x32_bf16 v[68:71], v[156:159], v[204:207], v[68:71]
	v_mfma_f32_16x16x32_bf16 v[120:123], v[152:155], v[178:181], v[120:123]
	v_mfma_f32_16x16x32_bf16 v[116:119], v[170:173], v[178:181], v[116:119]
	v_mfma_f32_16x16x32_bf16 v[104:107], v[152:155], v[192:195], v[104:107]
	v_mfma_f32_16x16x32_bf16 v[100:103], v[170:173], v[192:195], v[100:103]
	v_mfma_f32_16x16x32_bf16 v[88:91], v[152:155], v[200:203], v[88:91]
	v_mfma_f32_16x16x32_bf16 v[84:87], v[170:173], v[200:203], v[84:87]
	v_mfma_f32_16x16x32_bf16 v[72:75], v[152:155], v[208:211], v[72:75]
	v_mfma_f32_16x16x32_bf16 v[68:71], v[170:173], v[208:211], v[68:71]
	s_setprio 0
	s_barrier
	s_add_i32 s36, s81, s0
	v_lshl_add_u64 v[212:213], v[212:213], 0, s[70:71]
	s_mov_b32 m0, s36
	ds_read_b128 v[174:177], v186 offset:49152
	ds_read_b128 v[178:181], v186 offset:50176
	ds_read_b128 v[188:191], v186 offset:51200
	ds_read_b128 v[192:195], v186 offset:52224
	ds_read_b128 v[196:199], v186 offset:53248
	ds_read_b128 v[200:203], v186 offset:54272
	ds_read_b128 v[204:207], v186 offset:55296
	ds_read_b128 v[208:211], v186 offset:56320
	global_load_lds_dwordx4 v[212:213], off
	s_add_i32 m0, s36, 0x2000
	s_add_u32 s34, s34, 0x80080
	v_lshl_add_u64 v[212:213], v[214:215], 0, s[70:71]
	s_addc_u32 s35, s35, 0
	s_add_i32 s36, s83, s0
	global_load_lds_dwordx4 v[212:213], off
	v_lshl_add_u64 v[212:213], s[34:35], 0, v[162:163]
	s_mov_b32 m0, s36
	s_nop 0
	global_load_lds_dwordx4 v[212:213], off
	v_lshl_add_u64 v[212:213], s[34:35], 0, v[0:1]
	s_add_i32 m0, s36, 0x2000
	s_nop 0
	global_load_lds_dwordx4 v[212:213], off
	v_lshl_add_u64 v[212:213], v[216:217], 0, s[70:71]
	s_mov_b32 m0, s47
	s_nop 0
	global_load_lds_dwordx4 v[212:213], off
	v_lshl_add_u64 v[212:213], v[226:227], 0, s[70:71]
	s_mov_b32 m0, s51
	s_nop 0
	global_load_lds_dwordx4 v[212:213], off
	s_waitcnt vmcnt(8)
	s_waitcnt lgkmcnt(0)
	s_setprio 1
	s_barrier
	v_mfma_f32_16x16x32_bf16 v[64:67], v[132:135], v[174:177], v[64:67]
	v_mfma_f32_16x16x32_bf16 v[60:63], v[140:143], v[174:177], v[60:63]
	v_mfma_f32_16x16x32_bf16 v[48:51], v[132:135], v[188:191], v[48:51]
	v_mfma_f32_16x16x32_bf16 v[44:47], v[140:143], v[188:191], v[44:47]
	v_mfma_f32_16x16x32_bf16 v[32:35], v[132:135], v[196:199], v[32:35]
	v_mfma_f32_16x16x32_bf16 v[28:31], v[140:143], v[196:199], v[28:31]
	v_mfma_f32_16x16x32_bf16 v[16:19], v[132:135], v[204:207], v[16:19]
	v_mfma_f32_16x16x32_bf16 v[12:15], v[140:143], v[204:207], v[12:15]
	v_mfma_f32_16x16x32_bf16 v[64:67], v[136:139], v[178:181], v[64:67]
	v_mfma_f32_16x16x32_bf16 v[60:63], v[144:147], v[178:181], v[60:63]
	v_mfma_f32_16x16x32_bf16 v[48:51], v[136:139], v[192:195], v[48:51]
	v_mfma_f32_16x16x32_bf16 v[44:47], v[144:147], v[192:195], v[44:47]
	v_mfma_f32_16x16x32_bf16 v[32:35], v[136:139], v[200:203], v[32:35]
	v_mfma_f32_16x16x32_bf16 v[28:31], v[144:147], v[200:203], v[28:31]
	v_mfma_f32_16x16x32_bf16 v[16:19], v[136:139], v[208:211], v[16:19]
	v_mfma_f32_16x16x32_bf16 v[12:15], v[144:147], v[208:211], v[12:15]
	s_setprio 0
	s_setprio 1
	v_mfma_f32_16x16x32_bf16 v[56:59], v[148:151], v[174:177], v[56:59]
	v_mfma_f32_16x16x32_bf16 v[52:55], v[156:159], v[174:177], v[52:55]
	v_mfma_f32_16x16x32_bf16 v[40:43], v[148:151], v[188:191], v[40:43]
	v_mfma_f32_16x16x32_bf16 v[36:39], v[156:159], v[188:191], v[36:39]
	v_mfma_f32_16x16x32_bf16 v[24:27], v[148:151], v[196:199], v[24:27]
	v_mfma_f32_16x16x32_bf16 v[20:23], v[156:159], v[196:199], v[20:23]
	v_mfma_f32_16x16x32_bf16 v[8:11], v[148:151], v[204:207], v[8:11]
	v_mfma_f32_16x16x32_bf16 v[4:7], v[156:159], v[204:207], v[4:7]
	v_mfma_f32_16x16x32_bf16 v[56:59], v[152:155], v[178:181], v[56:59]
	v_mfma_f32_16x16x32_bf16 v[52:55], v[170:173], v[178:181], v[52:55]
	v_mfma_f32_16x16x32_bf16 v[40:43], v[152:155], v[192:195], v[40:43]
	v_mfma_f32_16x16x32_bf16 v[36:39], v[170:173], v[192:195], v[36:39]
	v_mfma_f32_16x16x32_bf16 v[24:27], v[152:155], v[200:203], v[24:27]
	v_mfma_f32_16x16x32_bf16 v[20:23], v[170:173], v[200:203], v[20:23]
	v_mfma_f32_16x16x32_bf16 v[8:11], v[152:155], v[208:211], v[8:11]
	v_mfma_f32_16x16x32_bf16 v[4:7], v[170:173], v[208:211], v[4:7]
	s_setprio 0
	s_barrier
	s_add_i32 s75, s75, 2
	s_add_u32 s30, s30, 0x100
	s_addc_u32 s31, s31, 0
	s_add_u32 s69, s69, 0x100
	s_addc_u32 s74, s74, 0
	s_cmp_gt_u32 s75, 29
	s_cbranch_scc0 .LBB0_975
	s_and_b64 vcc, exec, s[20:21]
	s_cbranch_vccz .LBB0_978
	s_barrier

.LBB0_1067:
	s_add_u32 s34, s26, s12
	s_addc_u32 s35, s27, s13
	s_add_u32 s34, s34, 0x100
	s_addc_u32 s35, s35, 0
	s_add_u32 s83, s42, s12
	s_addc_u32 s92, s75, s13
	s_add_i32 s93, 0, 0x10000
	s_cmpk_eq_i32 s12, 0xf00
	s_cselect_b32 s37, s25, s35
	s_cselect_b32 s36, s81, s34
	s_cselect_b32 s35, s23, s92
	s_cselect_b32 s34, s84, s83
	s_add_i32 s83, 0, 0x14000
	v_add_u32_e32 v148, s93, v189
	v_add_u32_e32 v176, s83, v189
	ds_read_b128 v[136:139], v148
	ds_read_b128 v[140:143], v148 offset:1024
	ds_read_b128 v[144:147], v148 offset:2048
	ds_read_b128 v[148:151], v148 offset:3072
	ds_read_b128 v[152:155], v176
	ds_read_b128 v[156:159], v176 offset:1024
	ds_read_b128 v[160:163], v176 offset:2048
	ds_read_b128 v[176:179], v176 offset:3072
	v_lshl_add_u64 v[184:185], v[132:133], 0, s[12:13]
	s_add_i32 m0, s39, 0xc000
	ds_read_b128 v[180:183], v192
	ds_read_b128 v[194:197], v192 offset:1024
	ds_read_b128 v[198:201], v192 offset:2048
	ds_read_b128 v[202:205], v192 offset:3072
	ds_read_b128 v[206:209], v192 offset:4096
	ds_read_b128 v[210:213], v192 offset:5120
	ds_read_b128 v[214:217], v192 offset:6144
	ds_read_b128 v[226:229], v192 offset:7168
	global_load_lds_dwordx4 v[184:185], off
	v_lshl_add_u64 v[184:185], v[134:135], 0, s[12:13]
	s_add_i32 m0, s39, 0xe000
	s_nop 0
	global_load_lds_dwordx4 v[184:185], off
	s_waitcnt vmcnt(8)
	s_waitcnt lgkmcnt(0)
	s_setprio 1
	s_barrier
	v_mfma_f32_16x16x32_bf16 v[8:11], v[136:139], v[180:183], v[8:11]
	v_mfma_f32_16x16x32_bf16 v[128:131], v[144:147], v[180:183], v[128:131]
	v_mfma_f32_16x16x32_bf16 v[124:127], v[136:139], v[198:201], v[124:127]
	v_mfma_f32_16x16x32_bf16 v[120:123], v[144:147], v[198:201], v[120:123]
	v_mfma_f32_16x16x32_bf16 v[116:119], v[136:139], v[206:209], v[116:119]
	v_mfma_f32_16x16x32_bf16 v[112:115], v[144:147], v[206:209], v[112:115]
	v_mfma_f32_16x16x32_bf16 v[108:111], v[136:139], v[214:217], v[108:111]
	v_mfma_f32_16x16x32_bf16 v[104:107], v[144:147], v[214:217], v[104:107]
	v_mfma_f32_16x16x32_bf16 v[8:11], v[140:143], v[194:197], v[8:11]
	v_mfma_f32_16x16x32_bf16 v[128:131], v[148:151], v[194:197], v[128:131]
	v_mfma_f32_16x16x32_bf16 v[124:127], v[140:143], v[202:205], v[124:127]
	v_mfma_f32_16x16x32_bf16 v[120:123], v[148:151], v[202:205], v[120:123]
	v_mfma_f32_16x16x32_bf16 v[116:119], v[140:143], v[210:213], v[116:119]
	v_mfma_f32_16x16x32_bf16 v[112:115], v[148:151], v[210:213], v[112:115]
	v_mfma_f32_16x16x32_bf16 v[108:111], v[140:143], v[226:229], v[108:111]
	v_mfma_f32_16x16x32_bf16 v[104:107], v[148:151], v[226:229], v[104:107]
	s_setprio 0
	s_setprio 1
	v_mfma_f32_16x16x32_bf16 v[100:103], v[152:155], v[180:183], v[100:103]
	v_mfma_f32_16x16x32_bf16 v[96:99], v[160:163], v[180:183], v[96:99]
	v_mfma_f32_16x16x32_bf16 v[92:95], v[152:155], v[198:201], v[92:95]
	v_mfma_f32_16x16x32_bf16 v[88:91], v[160:163], v[198:201], v[88:91]
	v_mfma_f32_16x16x32_bf16 v[84:87], v[152:155], v[206:209], v[84:87]
	v_mfma_f32_16x16x32_bf16 v[80:83], v[160:163], v[206:209], v[80:83]
	v_mfma_f32_16x16x32_bf16 v[76:79], v[152:155], v[214:217], v[76:79]
	v_mfma_f32_16x16x32_bf16 v[72:75], v[160:163], v[214:217], v[72:75]
	v_mfma_f32_16x16x32_bf16 v[100:103], v[156:159], v[194:197], v[100:103]
	v_mfma_f32_16x16x32_bf16 v[96:99], v[176:179], v[194:197], v[96:99]
	v_mfma_f32_16x16x32_bf16 v[92:95], v[156:159], v[202:205], v[92:95]
	v_mfma_f32_16x16x32_bf16 v[88:91], v[176:179], v[202:205], v[88:91]
	v_mfma_f32_16x16x32_bf16 v[84:87], v[156:159], v[210:213], v[84:87]
	v_mfma_f32_16x16x32_bf16 v[80:83], v[176:179], v[210:213], v[80:83]
	v_mfma_f32_16x16x32_bf16 v[76:79], v[156:159], v[226:229], v[76:79]
	v_mfma_f32_16x16x32_bf16 v[72:75], v[176:179], v[226:229], v[72:75]
	s_setprio 0
	s_barrier
	s_add_i32 s92, s93, s38
	v_lshl_add_u64 v[184:185], s[34:35], 0, v[164:165]
	s_mov_b32 m0, s92
	ds_read_b128 v[180:183], v192 offset:16384
	ds_read_b128 v[194:197], v192 offset:17408
	ds_read_b128 v[198:201], v192 offset:18432
	ds_read_b128 v[202:205], v192 offset:19456
	ds_read_b128 v[206:209], v192 offset:20480
	ds_read_b128 v[210:213], v192 offset:21504
	ds_read_b128 v[214:217], v192 offset:22528
	ds_read_b128 v[226:229], v192 offset:23552
	global_load_lds_dwordx4 v[184:185], off
	s_add_i32 m0, s92, 0x2000
	s_add_u32 s92, s34, 0x80000
	v_lshl_add_u64 v[230:231], s[34:35], 0, v[168:169]
	s_addc_u32 s93, s35, 0
	s_add_i32 s83, s83, s38
	global_load_lds_dwordx4 v[230:231], off
	v_lshl_add_u64 v[232:233], s[92:93], 0, v[164:165]
	s_mov_b32 m0, s83
	v_lshl_add_u64 v[234:235], s[36:37], 0, v[166:167]
	global_load_lds_dwordx4 v[232:233], off
	v_lshl_add_u64 v[232:233], s[92:93], 0, v[168:169]
	s_add_i32 m0, s83, 0x2000
	s_nop 0
	global_load_lds_dwordx4 v[232:233], off
	v_lshl_add_u64 v[232:233], s[36:37], 0, v[0:1]
	s_mov_b32 m0, s39
	s_nop 0
	global_load_lds_dwordx4 v[232:233], off
	s_mov_b32 m0, s43
	s_nop 0
	global_load_lds_dwordx4 v[234:235], off
	s_waitcnt vmcnt(8)
	s_waitcnt lgkmcnt(0)
	s_setprio 1
	s_barrier
	v_mfma_f32_16x16x32_bf16 v[68:71], v[136:139], v[180:183], v[68:71]
	v_mfma_f32_16x16x32_bf16 v[64:67], v[144:147], v[180:183], v[64:67]
	v_mfma_f32_16x16x32_bf16 v[60:63], v[136:139], v[198:201], v[60:63]
	v_mfma_f32_16x16x32_bf16 v[56:59], v[144:147], v[198:201], v[56:59]
	v_mfma_f32_16x16x32_bf16 v[52:55], v[136:139], v[206:209], v[52:55]
	v_mfma_f32_16x16x32_bf16 v[48:51], v[144:147], v[206:209], v[48:51]
	v_mfma_f32_16x16x32_bf16 v[44:47], v[136:139], v[214:217], v[44:47]
	v_mfma_f32_16x16x32_bf16 v[40:43], v[144:147], v[214:217], v[40:43]
	v_mfma_f32_16x16x32_bf16 v[68:71], v[140:143], v[194:197], v[68:71]
	v_mfma_f32_16x16x32_bf16 v[64:67], v[148:151], v[194:197], v[64:67]
	v_mfma_f32_16x16x32_bf16 v[60:63], v[140:143], v[202:205], v[60:63]
	v_mfma_f32_16x16x32_bf16 v[56:59], v[148:151], v[202:205], v[56:59]
	v_mfma_f32_16x16x32_bf16 v[52:55], v[140:143], v[210:213], v[52:55]
	v_mfma_f32_16x16x32_bf16 v[48:51], v[148:151], v[210:213], v[48:51]
	v_mfma_f32_16x16x32_bf16 v[44:47], v[140:143], v[226:229], v[44:47]
	v_mfma_f32_16x16x32_bf16 v[40:43], v[148:151], v[226:229], v[40:43]
	s_setprio 0
	s_setprio 1
	v_mfma_f32_16x16x32_bf16 v[36:39], v[152:155], v[180:183], v[36:39]
	v_mfma_f32_16x16x32_bf16 v[32:35], v[160:163], v[180:183], v[32:35]
	v_mfma_f32_16x16x32_bf16 v[28:31], v[152:155], v[198:201], v[28:31]
	v_mfma_f32_16x16x32_bf16 v[24:27], v[160:163], v[198:201], v[24:27]
	v_mfma_f32_16x16x32_bf16 v[20:23], v[152:155], v[206:209], v[20:23]
	v_mfma_f32_16x16x32_bf16 v[16:19], v[160:163], v[206:209], v[16:19]
	v_mfma_f32_16x16x32_bf16 v[12:15], v[152:155], v[214:217], v[12:15]
	v_mfma_f32_16x16x32_bf16 v[4:7], v[160:163], v[214:217], v[4:7]
	v_mfma_f32_16x16x32_bf16 v[36:39], v[156:159], v[194:197], v[36:39]
	v_mfma_f32_16x16x32_bf16 v[32:35], v[176:179], v[194:197], v[32:35]
	v_mfma_f32_16x16x32_bf16 v[28:31], v[156:159], v[202:205], v[28:31]
	v_mfma_f32_16x16x32_bf16 v[24:27], v[176:179], v[202:205], v[24:27]
	v_mfma_f32_16x16x32_bf16 v[20:23], v[156:159], v[210:213], v[20:23]
	v_mfma_f32_16x16x32_bf16 v[16:19], v[176:179], v[210:213], v[16:19]
	v_mfma_f32_16x16x32_bf16 v[12:15], v[156:159], v[226:229], v[12:15]
	v_mfma_f32_16x16x32_bf16 v[4:7], v[176:179], v[226:229], v[4:7]
	s_setprio 0
	s_barrier
	s_add_i32 s83, 0, 0x18000
	s_add_i32 s92, 0, 0x1c000
	v_add_u32_e32 v148, s83, v189
	v_add_u32_e32 v176, s92, v189
	ds_read_b128 v[136:139], v148
	ds_read_b128 v[140:143], v148 offset:1024
	ds_read_b128 v[144:147], v148 offset:2048
	ds_read_b128 v[148:151], v148 offset:3072
	ds_read_b128 v[152:155], v176
	ds_read_b128 v[156:159], v176 offset:1024
	ds_read_b128 v[160:163], v176 offset:2048
	ds_read_b128 v[176:179], v176 offset:3072
	s_add_u32 s36, s36, 0x80000
	s_addc_u32 s37, s37, 0
	s_mov_b32 m0, s46
	v_lshl_add_u64 v[236:237], s[36:37], 0, v[0:1]
	ds_read_b128 v[180:183], v192 offset:32768
	ds_read_b128 v[194:197], v192 offset:33792
	ds_read_b128 v[198:201], v192 offset:34816
	ds_read_b128 v[202:205], v192 offset:35840
	ds_read_b128 v[206:209], v192 offset:36864
	ds_read_b128 v[210:213], v192 offset:37888
	ds_read_b128 v[214:217], v192 offset:38912
	ds_read_b128 v[226:229], v192 offset:39936
	global_load_lds_dwordx4 v[236:237], off
	v_lshl_add_u64 v[236:237], s[36:37], 0, v[166:167]
	s_mov_b32 m0, s47
	s_nop 0
	global_load_lds_dwordx4 v[236:237], off
	s_waitcnt vmcnt(8)
	s_waitcnt lgkmcnt(0)
	s_setprio 1
	s_barrier
	v_mfma_f32_16x16x32_bf16 v[8:11], v[136:139], v[180:183], v[8:11]
	v_mfma_f32_16x16x32_bf16 v[128:131], v[144:147], v[180:183], v[128:131]
	v_mfma_f32_16x16x32_bf16 v[124:127], v[136:139], v[198:201], v[124:127]
	v_mfma_f32_16x16x32_bf16 v[120:123], v[144:147], v[198:201], v[120:123]
	v_mfma_f32_16x16x32_bf16 v[116:119], v[136:139], v[206:209], v[116:119]
	v_mfma_f32_16x16x32_bf16 v[112:115], v[144:147], v[206:209], v[112:115]
	v_mfma_f32_16x16x32_bf16 v[108:111], v[136:139], v[214:217], v[108:111]
	v_mfma_f32_16x16x32_bf16 v[104:107], v[144:147], v[214:217], v[104:107]
	v_mfma_f32_16x16x32_bf16 v[8:11], v[140:143], v[194:197], v[8:11]
	v_mfma_f32_16x16x32_bf16 v[128:131], v[148:151], v[194:197], v[128:131]
	v_mfma_f32_16x16x32_bf16 v[124:127], v[140:143], v[202:205], v[124:127]
	v_mfma_f32_16x16x32_bf16 v[120:123], v[148:151], v[202:205], v[120:123]
	v_mfma_f32_16x16x32_bf16 v[116:119], v[140:143], v[210:213], v[116:119]
	v_mfma_f32_16x16x32_bf16 v[112:115], v[148:151], v[210:213], v[112:115]
	v_mfma_f32_16x16x32_bf16 v[108:111], v[140:143], v[226:229], v[108:111]
	v_mfma_f32_16x16x32_bf16 v[104:107], v[148:151], v[226:229], v[104:107]
	s_setprio 0
	s_setprio 1
	v_mfma_f32_16x16x32_bf16 v[100:103], v[152:155], v[180:183], v[100:103]
	v_mfma_f32_16x16x32_bf16 v[96:99], v[160:163], v[180:183], v[96:99]
	v_mfma_f32_16x16x32_bf16 v[92:95], v[152:155], v[198:201], v[92:95]
	v_mfma_f32_16x16x32_bf16 v[88:91], v[160:163], v[198:201], v[88:91]
	v_mfma_f32_16x16x32_bf16 v[84:87], v[152:155], v[206:209], v[84:87]
	v_mfma_f32_16x16x32_bf16 v[80:83], v[160:163], v[206:209], v[80:83]
	v_mfma_f32_16x16x32_bf16 v[76:79], v[152:155], v[214:217], v[76:79]
	v_mfma_f32_16x16x32_bf16 v[72:75], v[160:163], v[214:217], v[72:75]
	v_mfma_f32_16x16x32_bf16 v[100:103], v[156:159], v[194:197], v[100:103]
	v_mfma_f32_16x16x32_bf16 v[96:99], v[176:179], v[194:197], v[96:99]
	v_mfma_f32_16x16x32_bf16 v[92:95], v[156:159], v[202:205], v[92:95]
	v_mfma_f32_16x16x32_bf16 v[88:91], v[176:179], v[202:205], v[88:91]
	v_mfma_f32_16x16x32_bf16 v[84:87], v[156:159], v[210:213], v[84:87]
	v_mfma_f32_16x16x32_bf16 v[80:83], v[176:179], v[210:213], v[80:83]
	v_mfma_f32_16x16x32_bf16 v[76:79], v[156:159], v[226:229], v[76:79]
	v_mfma_f32_16x16x32_bf16 v[72:75], v[176:179], v[226:229], v[72:75]
	s_setprio 0
	s_barrier
	s_add_i32 s36, s83, s38
	v_lshl_add_u64 v[184:185], v[184:185], 0, s[70:71]
	s_mov_b32 m0, s36
	ds_read_b128 v[180:183], v192 offset:49152
	ds_read_b128 v[194:197], v192 offset:50176
	ds_read_b128 v[198:201], v192 offset:51200
	ds_read_b128 v[202:205], v192 offset:52224
	ds_read_b128 v[206:209], v192 offset:53248
	ds_read_b128 v[210:213], v192 offset:54272
	ds_read_b128 v[214:217], v192 offset:55296
	ds_read_b128 v[226:229], v192 offset:56320
	global_load_lds_dwordx4 v[184:185], off
	s_add_i32 m0, s36, 0x2000
	s_add_u32 s34, s34, 0x80080
	v_lshl_add_u64 v[184:185], v[230:231], 0, s[70:71]
	s_addc_u32 s35, s35, 0
	s_add_i32 s36, s92, s38
	global_load_lds_dwordx4 v[184:185], off
	v_lshl_add_u64 v[184:185], s[34:35], 0, v[164:165]
	s_mov_b32 m0, s36
	s_nop 0
	global_load_lds_dwordx4 v[184:185], off
	v_lshl_add_u64 v[184:185], s[34:35], 0, v[168:169]
	s_add_i32 m0, s36, 0x2000
	s_nop 0
	global_load_lds_dwordx4 v[184:185], off
	v_lshl_add_u64 v[184:185], v[232:233], 0, s[70:71]
	s_mov_b32 m0, s51
	s_nop 0
	global_load_lds_dwordx4 v[184:185], off
	v_lshl_add_u64 v[184:185], v[234:235], 0, s[70:71]
	s_mov_b32 m0, s52
	s_nop 0
	global_load_lds_dwordx4 v[184:185], off
	s_waitcnt vmcnt(8)
	s_waitcnt lgkmcnt(0)
	s_setprio 1
	s_barrier
	v_mfma_f32_16x16x32_bf16 v[68:71], v[136:139], v[180:183], v[68:71]
	v_mfma_f32_16x16x32_bf16 v[64:67], v[144:147], v[180:183], v[64:67]
	v_mfma_f32_16x16x32_bf16 v[60:63], v[136:139], v[198:201], v[60:63]
	v_mfma_f32_16x16x32_bf16 v[56:59], v[144:147], v[198:201], v[56:59]
	v_mfma_f32_16x16x32_bf16 v[52:55], v[136:139], v[206:209], v[52:55]
	v_mfma_f32_16x16x32_bf16 v[48:51], v[144:147], v[206:209], v[48:51]
	v_mfma_f32_16x16x32_bf16 v[44:47], v[136:139], v[214:217], v[44:47]
	v_mfma_f32_16x16x32_bf16 v[40:43], v[144:147], v[214:217], v[40:43]
	v_mfma_f32_16x16x32_bf16 v[68:71], v[140:143], v[194:197], v[68:71]
	v_mfma_f32_16x16x32_bf16 v[64:67], v[148:151], v[194:197], v[64:67]
	v_mfma_f32_16x16x32_bf16 v[60:63], v[140:143], v[202:205], v[60:63]
	v_mfma_f32_16x16x32_bf16 v[56:59], v[148:151], v[202:205], v[56:59]
	v_mfma_f32_16x16x32_bf16 v[52:55], v[140:143], v[210:213], v[52:55]
	v_mfma_f32_16x16x32_bf16 v[48:51], v[148:151], v[210:213], v[48:51]
	v_mfma_f32_16x16x32_bf16 v[44:47], v[140:143], v[226:229], v[44:47]
	v_mfma_f32_16x16x32_bf16 v[40:43], v[148:151], v[226:229], v[40:43]
	s_setprio 0
	s_setprio 1
	v_mfma_f32_16x16x32_bf16 v[36:39], v[152:155], v[180:183], v[36:39]
	v_mfma_f32_16x16x32_bf16 v[32:35], v[160:163], v[180:183], v[32:35]
	v_mfma_f32_16x16x32_bf16 v[28:31], v[152:155], v[198:201], v[28:31]
	v_mfma_f32_16x16x32_bf16 v[24:27], v[160:163], v[198:201], v[24:27]
	v_mfma_f32_16x16x32_bf16 v[20:23], v[152:155], v[206:209], v[20:23]
	v_mfma_f32_16x16x32_bf16 v[16:19], v[160:163], v[206:209], v[16:19]
	v_mfma_f32_16x16x32_bf16 v[12:15], v[152:155], v[214:217], v[12:15]
	v_mfma_f32_16x16x32_bf16 v[4:7], v[160:163], v[214:217], v[4:7]
	v_mfma_f32_16x16x32_bf16 v[36:39], v[156:159], v[194:197], v[36:39]
	v_mfma_f32_16x16x32_bf16 v[32:35], v[176:179], v[194:197], v[32:35]
	v_mfma_f32_16x16x32_bf16 v[28:31], v[156:159], v[202:205], v[28:31]
	v_mfma_f32_16x16x32_bf16 v[24:27], v[176:179], v[202:205], v[24:27]
	v_mfma_f32_16x16x32_bf16 v[20:23], v[156:159], v[210:213], v[20:23]
	v_mfma_f32_16x16x32_bf16 v[16:19], v[176:179], v[210:213], v[16:19]
	v_mfma_f32_16x16x32_bf16 v[12:15], v[156:159], v[226:229], v[12:15]
	v_mfma_f32_16x16x32_bf16 v[4:7], v[176:179], v[226:229], v[4:7]
	s_setprio 0
	s_barrier
	s_add_i32 s85, s85, 2
	s_add_u32 s12, s12, 0x100
	s_addc_u32 s13, s13, 0
	s_cmp_gt_u32 s85, 29
	s_cbranch_scc0 .LBB0_1067
	s_and_b64 vcc, exec, s[20:21]
	s_cbranch_vccz .LBB0_1070
	s_barrier

.LBB0_1205:
	s_add_u32 s24, s22, 0x100
	s_addc_u32 s25, s23, 0
	s_add_i32 s67, 0, 0x10000
	s_cmpk_eq_i32 s66, 0x54
	s_cselect_b32 s29, s9, s25
	s_cselect_b32 s28, s8, s24
	s_cselect_b32 s27, s21, s54
	s_cselect_b32 s26, s20, s52
	s_add_i32 s69, 0, 0x14000
	v_add_u32_e32 v144, s67, v182
	v_add_u32_e32 v170, s69, v182
	ds_read_b128 v[132:135], v144
	ds_read_b128 v[136:139], v144 offset:1024
	ds_read_b128 v[140:143], v144 offset:2048
	ds_read_b128 v[144:147], v144 offset:3072
	ds_read_b128 v[148:151], v170
	ds_read_b128 v[152:155], v170 offset:1024
	ds_read_b128 v[156:159], v170 offset:2048
	ds_read_b128 v[170:173], v170 offset:3072
	v_lshl_add_u64 v[212:213], s[22:23], 0, v[166:167]
	s_add_i32 m0, s31, 0xc000
	ds_read_b128 v[174:177], v186
	ds_read_b128 v[178:181], v186 offset:1024
	ds_read_b128 v[188:191], v186 offset:2048
	ds_read_b128 v[192:195], v186 offset:3072
	ds_read_b128 v[196:199], v186 offset:4096
	ds_read_b128 v[200:203], v186 offset:5120
	ds_read_b128 v[204:207], v186 offset:6144
	ds_read_b128 v[208:211], v186 offset:7168
	global_load_lds_dwordx4 v[212:213], off
	v_lshl_add_u64 v[212:213], s[22:23], 0, v[168:169]
	s_add_i32 m0, s31, 0xe000
	s_nop 0
	global_load_lds_dwordx4 v[212:213], off
	s_waitcnt vmcnt(8)
	s_waitcnt lgkmcnt(0)
	s_setprio 1
	s_barrier
	v_mfma_f32_16x16x32_bf16 v[128:131], v[132:135], v[174:177], v[128:131]
	v_mfma_f32_16x16x32_bf16 v[124:127], v[140:143], v[174:177], v[124:127]
	v_mfma_f32_16x16x32_bf16 v[112:115], v[132:135], v[188:191], v[112:115]
	v_mfma_f32_16x16x32_bf16 v[108:111], v[140:143], v[188:191], v[108:111]
	v_mfma_f32_16x16x32_bf16 v[96:99], v[132:135], v[196:199], v[96:99]
	v_mfma_f32_16x16x32_bf16 v[92:95], v[140:143], v[196:199], v[92:95]
	v_mfma_f32_16x16x32_bf16 v[80:83], v[132:135], v[204:207], v[80:83]
	v_mfma_f32_16x16x32_bf16 v[76:79], v[140:143], v[204:207], v[76:79]
	v_mfma_f32_16x16x32_bf16 v[128:131], v[136:139], v[178:181], v[128:131]
	v_mfma_f32_16x16x32_bf16 v[124:127], v[144:147], v[178:181], v[124:127]
	v_mfma_f32_16x16x32_bf16 v[112:115], v[136:139], v[192:195], v[112:115]
	v_mfma_f32_16x16x32_bf16 v[108:111], v[144:147], v[192:195], v[108:111]
	v_mfma_f32_16x16x32_bf16 v[96:99], v[136:139], v[200:203], v[96:99]
	v_mfma_f32_16x16x32_bf16 v[92:95], v[144:147], v[200:203], v[92:95]
	v_mfma_f32_16x16x32_bf16 v[80:83], v[136:139], v[208:211], v[80:83]
	v_mfma_f32_16x16x32_bf16 v[76:79], v[144:147], v[208:211], v[76:79]
	s_setprio 0
	s_setprio 1
	v_mfma_f32_16x16x32_bf16 v[120:123], v[148:151], v[174:177], v[120:123]
	v_mfma_f32_16x16x32_bf16 v[116:119], v[156:159], v[174:177], v[116:119]
	v_mfma_f32_16x16x32_bf16 v[104:107], v[148:151], v[188:191], v[104:107]
	v_mfma_f32_16x16x32_bf16 v[100:103], v[156:159], v[188:191], v[100:103]
	v_mfma_f32_16x16x32_bf16 v[88:91], v[148:151], v[196:199], v[88:91]
	v_mfma_f32_16x16x32_bf16 v[84:87], v[156:159], v[196:199], v[84:87]
	v_mfma_f32_16x16x32_bf16 v[72:75], v[148:151], v[204:207], v[72:75]
	v_mfma_f32_16x16x32_bf16 v[68:71], v[156:159], v[204:207], v[68:71]
	v_mfma_f32_16x16x32_bf16 v[120:123], v[152:155], v[178:181], v[120:123]
	v_mfma_f32_16x16x32_bf16 v[116:119], v[170:173], v[178:181], v[116:119]
	v_mfma_f32_16x16x32_bf16 v[104:107], v[152:155], v[192:195], v[104:107]
	v_mfma_f32_16x16x32_bf16 v[100:103], v[170:173], v[192:195], v[100:103]
	v_mfma_f32_16x16x32_bf16 v[88:91], v[152:155], v[200:203], v[88:91]
	v_mfma_f32_16x16x32_bf16 v[84:87], v[170:173], v[200:203], v[84:87]
	v_mfma_f32_16x16x32_bf16 v[72:75], v[152:155], v[208:211], v[72:75]
	v_mfma_f32_16x16x32_bf16 v[68:71], v[170:173], v[208:211], v[68:71]
	s_setprio 0
	s_barrier
	s_add_i32 s22, s67, s30
	v_lshl_add_u64 v[212:213], s[26:27], 0, v[162:163]
	s_mov_b32 m0, s22
	ds_read_b128 v[174:177], v186 offset:16384
	ds_read_b128 v[178:181], v186 offset:17408
	ds_read_b128 v[188:191], v186 offset:18432
	ds_read_b128 v[192:195], v186 offset:19456
	ds_read_b128 v[196:199], v186 offset:20480
	ds_read_b128 v[200:203], v186 offset:21504
	ds_read_b128 v[204:207], v186 offset:22528
	ds_read_b128 v[208:211], v186 offset:23552
	global_load_lds_dwordx4 v[212:213], off
	s_add_i32 m0, s22, 0x2000
	s_add_u32 s22, s26, 0x160000
	v_lshl_add_u64 v[214:215], s[26:27], 0, v[0:1]
	s_addc_u32 s23, s27, 0
	s_add_i32 s67, s69, s30
	global_load_lds_dwordx4 v[214:215], off
	v_lshl_add_u64 v[216:217], s[22:23], 0, v[162:163]
	s_mov_b32 m0, s67
	v_lshl_add_u64 v[226:227], s[28:29], 0, v[160:161]
	global_load_lds_dwordx4 v[216:217], off
	v_lshl_add_u64 v[216:217], s[22:23], 0, v[0:1]
	s_add_i32 m0, s67, 0x2000
	s_nop 0
	global_load_lds_dwordx4 v[216:217], off
	v_lshl_add_u64 v[216:217], s[28:29], 0, v[164:165]
	s_mov_b32 m0, s31
	s_nop 0
	global_load_lds_dwordx4 v[216:217], off
	s_mov_b32 m0, s34
	s_nop 0
	global_load_lds_dwordx4 v[226:227], off
	s_waitcnt vmcnt(8)
	s_waitcnt lgkmcnt(0)
	s_setprio 1
	s_barrier
	v_mfma_f32_16x16x32_bf16 v[64:67], v[132:135], v[174:177], v[64:67]
	v_mfma_f32_16x16x32_bf16 v[60:63], v[140:143], v[174:177], v[60:63]
	v_mfma_f32_16x16x32_bf16 v[48:51], v[132:135], v[188:191], v[48:51]
	v_mfma_f32_16x16x32_bf16 v[44:47], v[140:143], v[188:191], v[44:47]
	v_mfma_f32_16x16x32_bf16 v[32:35], v[132:135], v[196:199], v[32:35]
	v_mfma_f32_16x16x32_bf16 v[28:31], v[140:143], v[196:199], v[28:31]
	v_mfma_f32_16x16x32_bf16 v[16:19], v[132:135], v[204:207], v[16:19]
	v_mfma_f32_16x16x32_bf16 v[12:15], v[140:143], v[204:207], v[12:15]
	v_mfma_f32_16x16x32_bf16 v[64:67], v[136:139], v[178:181], v[64:67]
	v_mfma_f32_16x16x32_bf16 v[60:63], v[144:147], v[178:181], v[60:63]
	v_mfma_f32_16x16x32_bf16 v[48:51], v[136:139], v[192:195], v[48:51]
	v_mfma_f32_16x16x32_bf16 v[44:47], v[144:147], v[192:195], v[44:47]
	v_mfma_f32_16x16x32_bf16 v[32:35], v[136:139], v[200:203], v[32:35]
	v_mfma_f32_16x16x32_bf16 v[28:31], v[144:147], v[200:203], v[28:31]
	v_mfma_f32_16x16x32_bf16 v[16:19], v[136:139], v[208:211], v[16:19]
	v_mfma_f32_16x16x32_bf16 v[12:15], v[144:147], v[208:211], v[12:15]
	s_setprio 0
	s_setprio 1
	v_mfma_f32_16x16x32_bf16 v[56:59], v[148:151], v[174:177], v[56:59]
	v_mfma_f32_16x16x32_bf16 v[52:55], v[156:159], v[174:177], v[52:55]
	v_mfma_f32_16x16x32_bf16 v[40:43], v[148:151], v[188:191], v[40:43]
	v_mfma_f32_16x16x32_bf16 v[36:39], v[156:159], v[188:191], v[36:39]
	v_mfma_f32_16x16x32_bf16 v[24:27], v[148:151], v[196:199], v[24:27]
	v_mfma_f32_16x16x32_bf16 v[20:23], v[156:159], v[196:199], v[20:23]
	v_mfma_f32_16x16x32_bf16 v[8:11], v[148:151], v[204:207], v[8:11]
	v_mfma_f32_16x16x32_bf16 v[4:7], v[156:159], v[204:207], v[4:7]
	v_mfma_f32_16x16x32_bf16 v[56:59], v[152:155], v[178:181], v[56:59]
	v_mfma_f32_16x16x32_bf16 v[52:55], v[170:173], v[178:181], v[52:55]
	v_mfma_f32_16x16x32_bf16 v[40:43], v[152:155], v[192:195], v[40:43]
	v_mfma_f32_16x16x32_bf16 v[36:39], v[170:173], v[192:195], v[36:39]
	v_mfma_f32_16x16x32_bf16 v[24:27], v[152:155], v[200:203], v[24:27]
	v_mfma_f32_16x16x32_bf16 v[20:23], v[170:173], v[200:203], v[20:23]
	v_mfma_f32_16x16x32_bf16 v[8:11], v[152:155], v[208:211], v[8:11]
	v_mfma_f32_16x16x32_bf16 v[4:7], v[170:173], v[208:211], v[4:7]
	s_setprio 0
	s_barrier
	s_add_i32 s67, 0, 0x18000
	s_add_i32 s69, 0, 0x1c000
	v_add_u32_e32 v144, s67, v182
	v_add_u32_e32 v170, s69, v182
	ds_read_b128 v[132:135], v144
	ds_read_b128 v[136:139], v144 offset:1024
	ds_read_b128 v[140:143], v144 offset:2048
	ds_read_b128 v[144:147], v144 offset:3072
	ds_read_b128 v[148:151], v170
	ds_read_b128 v[152:155], v170 offset:1024
	ds_read_b128 v[156:159], v170 offset:2048
	ds_read_b128 v[170:173], v170 offset:3072
	s_add_u32 s22, s28, 0x160000
	s_addc_u32 s23, s29, 0
	s_mov_b32 m0, s35
	v_lshl_add_u64 v[228:229], s[22:23], 0, v[164:165]
	ds_read_b128 v[174:177], v186 offset:32768
	ds_read_b128 v[178:181], v186 offset:33792
	ds_read_b128 v[188:191], v186 offset:34816
	ds_read_b128 v[192:195], v186 offset:35840
	ds_read_b128 v[196:199], v186 offset:36864
	ds_read_b128 v[200:203], v186 offset:37888
	ds_read_b128 v[204:207], v186 offset:38912
	ds_read_b128 v[208:211], v186 offset:39936
	global_load_lds_dwordx4 v[228:229], off
	v_lshl_add_u64 v[228:229], s[22:23], 0, v[160:161]
	s_mov_b32 m0, s36
	s_nop 0
	global_load_lds_dwordx4 v[228:229], off
	s_waitcnt vmcnt(8)
	s_waitcnt lgkmcnt(0)
	s_setprio 1
	s_barrier
	v_mfma_f32_16x16x32_bf16 v[128:131], v[132:135], v[174:177], v[128:131]
	v_mfma_f32_16x16x32_bf16 v[124:127], v[140:143], v[174:177], v[124:127]
	v_mfma_f32_16x16x32_bf16 v[112:115], v[132:135], v[188:191], v[112:115]
	v_mfma_f32_16x16x32_bf16 v[108:111], v[140:143], v[188:191], v[108:111]
	v_mfma_f32_16x16x32_bf16 v[96:99], v[132:135], v[196:199], v[96:99]
	v_mfma_f32_16x16x32_bf16 v[92:95], v[140:143], v[196:199], v[92:95]
	v_mfma_f32_16x16x32_bf16 v[80:83], v[132:135], v[204:207], v[80:83]
	v_mfma_f32_16x16x32_bf16 v[76:79], v[140:143], v[204:207], v[76:79]
	v_mfma_f32_16x16x32_bf16 v[128:131], v[136:139], v[178:181], v[128:131]
	v_mfma_f32_16x16x32_bf16 v[124:127], v[144:147], v[178:181], v[124:127]
	v_mfma_f32_16x16x32_bf16 v[112:115], v[136:139], v[192:195], v[112:115]
	v_mfma_f32_16x16x32_bf16 v[108:111], v[144:147], v[192:195], v[108:111]
	v_mfma_f32_16x16x32_bf16 v[96:99], v[136:139], v[200:203], v[96:99]
	v_mfma_f32_16x16x32_bf16 v[92:95], v[144:147], v[200:203], v[92:95]
	v_mfma_f32_16x16x32_bf16 v[80:83], v[136:139], v[208:211], v[80:83]
	v_mfma_f32_16x16x32_bf16 v[76:79], v[144:147], v[208:211], v[76:79]
	s_setprio 0
	s_setprio 1
	v_mfma_f32_16x16x32_bf16 v[120:123], v[148:151], v[174:177], v[120:123]
	v_mfma_f32_16x16x32_bf16 v[116:119], v[156:159], v[174:177], v[116:119]
	v_mfma_f32_16x16x32_bf16 v[104:107], v[148:151], v[188:191], v[104:107]
	v_mfma_f32_16x16x32_bf16 v[100:103], v[156:159], v[188:191], v[100:103]
	v_mfma_f32_16x16x32_bf16 v[88:91], v[148:151], v[196:199], v[88:91]
	v_mfma_f32_16x16x32_bf16 v[84:87], v[156:159], v[196:199], v[84:87]
	v_mfma_f32_16x16x32_bf16 v[72:75], v[148:151], v[204:207], v[72:75]
	v_mfma_f32_16x16x32_bf16 v[68:71], v[156:159], v[204:207], v[68:71]
	v_mfma_f32_16x16x32_bf16 v[120:123], v[152:155], v[178:181], v[120:123]
	v_mfma_f32_16x16x32_bf16 v[116:119], v[170:173], v[178:181], v[116:119]
	v_mfma_f32_16x16x32_bf16 v[104:107], v[152:155], v[192:195], v[104:107]
	v_mfma_f32_16x16x32_bf16 v[100:103], v[170:173], v[192:195], v[100:103]
	v_mfma_f32_16x16x32_bf16 v[88:91], v[152:155], v[200:203], v[88:91]
	v_mfma_f32_16x16x32_bf16 v[84:87], v[170:173], v[200:203], v[84:87]
	v_mfma_f32_16x16x32_bf16 v[72:75], v[152:155], v[208:211], v[72:75]
	v_mfma_f32_16x16x32_bf16 v[68:71], v[170:173], v[208:211], v[68:71]
	s_setprio 0
	s_barrier
	s_add_i32 s22, s67, s30
	v_lshl_add_u64 v[212:213], v[212:213], 0, s[70:71]
	s_mov_b32 m0, s22
	ds_read_b128 v[174:177], v186 offset:49152
	ds_read_b128 v[178:181], v186 offset:50176
	ds_read_b128 v[188:191], v186 offset:51200
	ds_read_b128 v[192:195], v186 offset:52224
	ds_read_b128 v[196:199], v186 offset:53248
	ds_read_b128 v[200:203], v186 offset:54272
	ds_read_b128 v[204:207], v186 offset:55296
	ds_read_b128 v[208:211], v186 offset:56320
	global_load_lds_dwordx4 v[212:213], off
	s_add_i32 m0, s22, 0x2000
	s_add_u32 s22, s26, 0x160080
	v_lshl_add_u64 v[212:213], v[214:215], 0, s[70:71]
	s_addc_u32 s23, s27, 0
	s_add_i32 s26, s69, s30
	global_load_lds_dwordx4 v[212:213], off
	v_lshl_add_u64 v[212:213], s[22:23], 0, v[162:163]
	s_mov_b32 m0, s26
	s_nop 0
	global_load_lds_dwordx4 v[212:213], off
	v_lshl_add_u64 v[212:213], s[22:23], 0, v[0:1]
	s_add_i32 m0, s26, 0x2000
	s_nop 0
	global_load_lds_dwordx4 v[212:213], off
	v_lshl_add_u64 v[212:213], v[216:217], 0, s[70:71]
	s_mov_b32 m0, s38
	s_nop 0
	global_load_lds_dwordx4 v[212:213], off
	v_lshl_add_u64 v[212:213], v[226:227], 0, s[70:71]
	s_mov_b32 m0, s39
	s_nop 0
	global_load_lds_dwordx4 v[212:213], off
	s_waitcnt vmcnt(8)
	s_waitcnt lgkmcnt(0)
	s_setprio 1
	s_barrier
	v_mfma_f32_16x16x32_bf16 v[64:67], v[132:135], v[174:177], v[64:67]
	v_mfma_f32_16x16x32_bf16 v[60:63], v[140:143], v[174:177], v[60:63]
	v_mfma_f32_16x16x32_bf16 v[48:51], v[132:135], v[188:191], v[48:51]
	v_mfma_f32_16x16x32_bf16 v[44:47], v[140:143], v[188:191], v[44:47]
	v_mfma_f32_16x16x32_bf16 v[32:35], v[132:135], v[196:199], v[32:35]
	v_mfma_f32_16x16x32_bf16 v[28:31], v[140:143], v[196:199], v[28:31]
	v_mfma_f32_16x16x32_bf16 v[16:19], v[132:135], v[204:207], v[16:19]
	v_mfma_f32_16x16x32_bf16 v[12:15], v[140:143], v[204:207], v[12:15]
	v_mfma_f32_16x16x32_bf16 v[64:67], v[136:139], v[178:181], v[64:67]
	v_mfma_f32_16x16x32_bf16 v[60:63], v[144:147], v[178:181], v[60:63]
	v_mfma_f32_16x16x32_bf16 v[48:51], v[136:139], v[192:195], v[48:51]
	v_mfma_f32_16x16x32_bf16 v[44:47], v[144:147], v[192:195], v[44:47]
	v_mfma_f32_16x16x32_bf16 v[32:35], v[136:139], v[200:203], v[32:35]
	v_mfma_f32_16x16x32_bf16 v[28:31], v[144:147], v[200:203], v[28:31]
	v_mfma_f32_16x16x32_bf16 v[16:19], v[136:139], v[208:211], v[16:19]
	v_mfma_f32_16x16x32_bf16 v[12:15], v[144:147], v[208:211], v[12:15]
	s_setprio 0
	s_setprio 1
	v_mfma_f32_16x16x32_bf16 v[56:59], v[148:151], v[174:177], v[56:59]
	v_mfma_f32_16x16x32_bf16 v[52:55], v[156:159], v[174:177], v[52:55]
	v_mfma_f32_16x16x32_bf16 v[40:43], v[148:151], v[188:191], v[40:43]
	v_mfma_f32_16x16x32_bf16 v[36:39], v[156:159], v[188:191], v[36:39]
	v_mfma_f32_16x16x32_bf16 v[24:27], v[148:151], v[196:199], v[24:27]
	v_mfma_f32_16x16x32_bf16 v[20:23], v[156:159], v[196:199], v[20:23]
	v_mfma_f32_16x16x32_bf16 v[8:11], v[148:151], v[204:207], v[8:11]
	v_mfma_f32_16x16x32_bf16 v[4:7], v[156:159], v[204:207], v[4:7]
	v_mfma_f32_16x16x32_bf16 v[56:59], v[152:155], v[178:181], v[56:59]
	v_mfma_f32_16x16x32_bf16 v[52:55], v[170:173], v[178:181], v[52:55]
	v_mfma_f32_16x16x32_bf16 v[40:43], v[152:155], v[192:195], v[40:43]
	v_mfma_f32_16x16x32_bf16 v[36:39], v[170:173], v[192:195], v[36:39]
	v_mfma_f32_16x16x32_bf16 v[24:27], v[152:155], v[200:203], v[24:27]
	v_mfma_f32_16x16x32_bf16 v[20:23], v[170:173], v[200:203], v[20:23]
	v_mfma_f32_16x16x32_bf16 v[8:11], v[152:155], v[208:211], v[8:11]
	v_mfma_f32_16x16x32_bf16 v[4:7], v[170:173], v[208:211], v[4:7]
	s_setprio 0
	s_barrier
	s_add_i32 s66, s66, 2
	s_add_u32 s52, s52, 0x100
	s_addc_u32 s54, s54, 0
	s_cmpk_gt_u32 s66, 0x55
	s_mov_b64 s[22:23], s[24:25]
	s_cbranch_scc0 .LBB0_1205
	s_and_b64 vcc, exec, s[18:19]
	s_cbranch_vccz .LBB0_1208
	s_barrier
